# GEMM K-loops: last 2 of the 6 LDS-DMA issues of each SP2 super-phase moved from the load segment into the MFMA segment (vmcnt 8->6)
# speedup vs baseline: 1.0065x; 1.0029x over previous
.LBB0_166:
	ds_read_b128 v[128:131], v189
	ds_read_b128 v[132:135], v189 offset:1024
	ds_read_b128 v[136:139], v189 offset:2048
	ds_read_b128 v[140:143], v189 offset:3072
	ds_read_b128 v[166:169], v189 offset:16384
	ds_read_b128 v[170:173], v189 offset:17408
	ds_read_b128 v[174:177], v189 offset:18432
	ds_read_b128 v[192:195], v189 offset:19456
	s_add_u32 s23, s26, 0xfffc0080
	s_addc_u32 s28, s27, -1
	s_cmp_eq_u32 s53, 12
	s_cselect_b32 s31, s7, s28
	s_cselect_b32 s30, s19, s23
	s_cselect_b32 s29, s17, s52
	s_cselect_b32 s28, s50, s51
	s_add_i32 m0, s15, 0xc000
	ds_read_b128 v[196:199], v190
	ds_read_b128 v[200:203], v190 offset:1024
	ds_read_b128 v[204:207], v190 offset:2048
	ds_read_b128 v[208:211], v190 offset:3072
	ds_read_b128 v[212:215], v190 offset:4096
	ds_read_b128 v[216:219], v190 offset:5120
	ds_read_b128 v[220:223], v190 offset:6144
	ds_read_b128 v[224:227], v190 offset:7168
	global_load_lds_dwordx4 v144, s[26:27]
	s_add_i32 m0, s15, 0xe000
	v_mov_b32_e32 v149, v145
	global_load_lds_dwordx4 v148, s[26:27]
	s_waitcnt vmcnt(8)
	s_waitcnt lgkmcnt(0)
	s_barrier
	s_setprio 1
	s_waitcnt lgkmcnt(0)
	v_mfma_f32_16x16x32_bf16 v[124:127], v[128:131], v[196:199], v[124:127]
	v_mfma_f32_16x16x32_bf16 v[120:123], v[136:139], v[196:199], v[120:123]
	v_mfma_f32_16x16x32_bf16 v[116:119], v[128:131], v[204:207], v[116:119]
	v_mfma_f32_16x16x32_bf16 v[112:115], v[136:139], v[204:207], v[112:115]
	v_mfma_f32_16x16x32_bf16 v[100:103], v[128:131], v[212:215], v[100:103]
	v_mfma_f32_16x16x32_bf16 v[96:99], v[136:139], v[212:215], v[96:99]
	v_mfma_f32_16x16x32_bf16 v[84:87], v[128:131], v[220:223], v[84:87]
	v_mfma_f32_16x16x32_bf16 v[80:83], v[136:139], v[220:223], v[80:83]
	v_mfma_f32_16x16x32_bf16 v[124:127], v[132:135], v[200:203], v[124:127]
	v_mfma_f32_16x16x32_bf16 v[120:123], v[140:143], v[200:203], v[120:123]
	v_mfma_f32_16x16x32_bf16 v[116:119], v[132:135], v[208:211], v[116:119]
	v_mfma_f32_16x16x32_bf16 v[112:115], v[140:143], v[208:211], v[112:115]
	v_mfma_f32_16x16x32_bf16 v[100:103], v[132:135], v[216:219], v[100:103]
	v_mfma_f32_16x16x32_bf16 v[96:99], v[140:143], v[216:219], v[96:99]
	v_mfma_f32_16x16x32_bf16 v[84:87], v[132:135], v[224:227], v[84:87]
	v_mfma_f32_16x16x32_bf16 v[80:83], v[140:143], v[224:227], v[80:83]
	s_setprio 0
	s_setprio 1
	v_mfma_f32_16x16x32_bf16 v[108:111], v[166:169], v[196:199], v[108:111]
	v_mfma_f32_16x16x32_bf16 v[104:107], v[174:177], v[196:199], v[104:107]
	v_mfma_f32_16x16x32_bf16 v[92:95], v[166:169], v[204:207], v[92:95]
	v_mfma_f32_16x16x32_bf16 v[88:91], v[174:177], v[204:207], v[88:91]
	v_mfma_f32_16x16x32_bf16 v[76:79], v[166:169], v[212:215], v[76:79]
	v_mfma_f32_16x16x32_bf16 v[72:75], v[174:177], v[212:215], v[72:75]
	v_mfma_f32_16x16x32_bf16 v[68:71], v[166:169], v[220:223], v[68:71]
	v_mfma_f32_16x16x32_bf16 v[64:67], v[174:177], v[220:223], v[64:67]
	v_mfma_f32_16x16x32_bf16 v[108:111], v[170:173], v[200:203], v[108:111]
	v_mfma_f32_16x16x32_bf16 v[104:107], v[192:195], v[200:203], v[104:107]
	v_mfma_f32_16x16x32_bf16 v[92:95], v[170:173], v[208:211], v[92:95]
	v_mfma_f32_16x16x32_bf16 v[88:91], v[192:195], v[208:211], v[88:91]
	v_mfma_f32_16x16x32_bf16 v[76:79], v[170:173], v[216:219], v[76:79]
	v_mfma_f32_16x16x32_bf16 v[72:75], v[192:195], v[216:219], v[72:75]
	v_mfma_f32_16x16x32_bf16 v[68:71], v[170:173], v[224:227], v[68:71]
	v_mfma_f32_16x16x32_bf16 v[64:67], v[192:195], v[224:227], v[64:67]
	s_setprio 0
	s_barrier
	s_mov_b32 m0, s34
	ds_read_b128 v[196:199], v190 offset:16384
	ds_read_b128 v[200:203], v190 offset:17408
	ds_read_b128 v[204:207], v190 offset:18432
	ds_read_b128 v[208:211], v190 offset:19456
	ds_read_b128 v[212:215], v190 offset:20480
	ds_read_b128 v[216:219], v190 offset:21504
	ds_read_b128 v[220:223], v190 offset:22528
	ds_read_b128 v[224:227], v190 offset:23552
	global_load_lds_dwordx4 v146, s[28:29]
	s_mov_b32 m0, s35
	s_add_u32 s54, s28, 0x40000
	global_load_lds_dwordx4 v150, s[28:29]
	s_addc_u32 s55, s29, 0
	s_mov_b32 m0, s36
	v_mov_b32_e32 v147, v145
	global_load_lds_dwordx4 v146, s[54:55]
	s_mov_b32 m0, s37
	v_mov_b32_e32 v151, v145
	global_load_lds_dwordx4 v150, s[54:55]
	s_waitcnt vmcnt(6)
	s_waitcnt lgkmcnt(0)
	s_barrier
	s_setprio 1
	s_waitcnt lgkmcnt(0)
	v_mfma_f32_16x16x32_bf16 v[60:63], v[128:131], v[196:199], v[60:63]
	v_mfma_f32_16x16x32_bf16 v[56:59], v[136:139], v[196:199], v[56:59]
	s_mov_b32 m0, s15
	v_lshl_add_u64 v[180:181], s[28:29], 0, v[146:147]
	v_mfma_f32_16x16x32_bf16 v[52:55], v[128:131], v[204:207], v[52:55]
	global_load_lds_dwordx4 v144, s[30:31]
	v_mfma_f32_16x16x32_bf16 v[48:51], v[136:139], v[204:207], v[48:51]
	v_mfma_f32_16x16x32_bf16 v[36:39], v[128:131], v[212:215], v[36:39]
	v_mfma_f32_16x16x32_bf16 v[32:35], v[136:139], v[212:215], v[32:35]
	v_mfma_f32_16x16x32_bf16 v[20:23], v[128:131], v[220:223], v[20:23]
	v_mfma_f32_16x16x32_bf16 v[16:19], v[136:139], v[220:223], v[16:19]
	v_mfma_f32_16x16x32_bf16 v[60:63], v[132:135], v[200:203], v[60:63]
	v_mfma_f32_16x16x32_bf16 v[56:59], v[140:143], v[200:203], v[56:59]
	v_mfma_f32_16x16x32_bf16 v[52:55], v[132:135], v[208:211], v[52:55]
	v_mfma_f32_16x16x32_bf16 v[48:51], v[140:143], v[208:211], v[48:51]
	v_mfma_f32_16x16x32_bf16 v[36:39], v[132:135], v[216:219], v[36:39]
	v_mfma_f32_16x16x32_bf16 v[32:35], v[140:143], v[216:219], v[32:35]
	v_mfma_f32_16x16x32_bf16 v[20:23], v[132:135], v[224:227], v[20:23]
	v_mfma_f32_16x16x32_bf16 v[16:19], v[140:143], v[224:227], v[16:19]
	s_mov_b32 m0, s38
	v_lshl_add_u64 v[228:229], s[28:29], 0, v[150:151]
	s_setprio 0
	s_setprio 1
	v_mfma_f32_16x16x32_bf16 v[44:47], v[166:169], v[196:199], v[44:47]
	global_load_lds_dwordx4 v148, s[30:31]
	v_lshl_add_u64 v[230:231], s[30:31], 0, v[144:145]
	v_lshl_add_u64 v[232:233], s[30:31], 0, v[148:149]
	v_mfma_f32_16x16x32_bf16 v[40:43], v[174:177], v[196:199], v[40:43]
	v_mfma_f32_16x16x32_bf16 v[28:31], v[166:169], v[204:207], v[28:31]
	v_mfma_f32_16x16x32_bf16 v[24:27], v[174:177], v[204:207], v[24:27]
	v_mfma_f32_16x16x32_bf16 v[12:15], v[166:169], v[212:215], v[12:15]
	v_mfma_f32_16x16x32_bf16 v[8:11], v[174:177], v[212:215], v[8:11]
	v_mfma_f32_16x16x32_bf16 v[4:7], v[166:169], v[220:223], v[4:7]
	v_mfma_f32_16x16x32_bf16 v[0:3], v[174:177], v[220:223], v[0:3]
	v_mfma_f32_16x16x32_bf16 v[44:47], v[170:173], v[200:203], v[44:47]
	v_mfma_f32_16x16x32_bf16 v[40:43], v[192:195], v[200:203], v[40:43]
	v_mfma_f32_16x16x32_bf16 v[28:31], v[170:173], v[208:211], v[28:31]
	v_mfma_f32_16x16x32_bf16 v[24:27], v[192:195], v[208:211], v[24:27]
	v_mfma_f32_16x16x32_bf16 v[12:15], v[170:173], v[216:219], v[12:15]
	v_mfma_f32_16x16x32_bf16 v[8:11], v[192:195], v[216:219], v[8:11]
	v_mfma_f32_16x16x32_bf16 v[4:7], v[170:173], v[224:227], v[4:7]
	v_mfma_f32_16x16x32_bf16 v[0:3], v[192:195], v[224:227], v[0:3]
	s_setprio 0
	s_barrier
	ds_read_b128 v[128:131], v189 offset:32768
	ds_read_b128 v[132:135], v189 offset:33792
	ds_read_b128 v[136:139], v189 offset:34816
	ds_read_b128 v[140:143], v189 offset:35840
	ds_read_b128 v[166:169], v189 offset:49152
	ds_read_b128 v[170:173], v189 offset:50176
	ds_read_b128 v[174:177], v189 offset:51200
	ds_read_b128 v[192:195], v189 offset:52224
	s_add_u32 s30, s30, 0x40000
	s_addc_u32 s31, s31, 0
	s_mov_b32 m0, s39
	ds_read_b128 v[196:199], v190 offset:32768
	ds_read_b128 v[200:203], v190 offset:33792
	ds_read_b128 v[204:207], v190 offset:34816
	ds_read_b128 v[208:211], v190 offset:35840
	ds_read_b128 v[212:215], v190 offset:36864
	ds_read_b128 v[216:219], v190 offset:37888
	ds_read_b128 v[220:223], v190 offset:38912
	ds_read_b128 v[224:227], v190 offset:39936
	global_load_lds_dwordx4 v144, s[30:31]
	s_mov_b32 m0, s40
	s_nop 0
	global_load_lds_dwordx4 v148, s[30:31]
	s_waitcnt vmcnt(8)
	s_waitcnt lgkmcnt(0)
	s_barrier
	s_setprio 1
	s_waitcnt lgkmcnt(0)
	v_mfma_f32_16x16x32_bf16 v[124:127], v[128:131], v[196:199], v[124:127]
	v_mfma_f32_16x16x32_bf16 v[120:123], v[136:139], v[196:199], v[120:123]
	v_mfma_f32_16x16x32_bf16 v[116:119], v[128:131], v[204:207], v[116:119]
	v_mfma_f32_16x16x32_bf16 v[112:115], v[136:139], v[204:207], v[112:115]
	v_mfma_f32_16x16x32_bf16 v[100:103], v[128:131], v[212:215], v[100:103]
	v_mfma_f32_16x16x32_bf16 v[96:99], v[136:139], v[212:215], v[96:99]
	v_mfma_f32_16x16x32_bf16 v[84:87], v[128:131], v[220:223], v[84:87]
	v_mfma_f32_16x16x32_bf16 v[80:83], v[136:139], v[220:223], v[80:83]
	v_mfma_f32_16x16x32_bf16 v[124:127], v[132:135], v[200:203], v[124:127]
	v_mfma_f32_16x16x32_bf16 v[120:123], v[140:143], v[200:203], v[120:123]
	v_mfma_f32_16x16x32_bf16 v[116:119], v[132:135], v[208:211], v[116:119]
	v_mfma_f32_16x16x32_bf16 v[112:115], v[140:143], v[208:211], v[112:115]
	v_mfma_f32_16x16x32_bf16 v[100:103], v[132:135], v[216:219], v[100:103]
	v_mfma_f32_16x16x32_bf16 v[96:99], v[140:143], v[216:219], v[96:99]
	v_mfma_f32_16x16x32_bf16 v[84:87], v[132:135], v[224:227], v[84:87]
	v_mfma_f32_16x16x32_bf16 v[80:83], v[140:143], v[224:227], v[80:83]
	s_setprio 0
	s_setprio 1
	v_mfma_f32_16x16x32_bf16 v[108:111], v[166:169], v[196:199], v[108:111]
	v_mfma_f32_16x16x32_bf16 v[104:107], v[174:177], v[196:199], v[104:107]
	v_mfma_f32_16x16x32_bf16 v[92:95], v[166:169], v[204:207], v[92:95]
	v_mfma_f32_16x16x32_bf16 v[88:91], v[174:177], v[204:207], v[88:91]
	v_mfma_f32_16x16x32_bf16 v[76:79], v[166:169], v[212:215], v[76:79]
	v_mfma_f32_16x16x32_bf16 v[72:75], v[174:177], v[212:215], v[72:75]
	v_mfma_f32_16x16x32_bf16 v[68:71], v[166:169], v[220:223], v[68:71]
	v_mfma_f32_16x16x32_bf16 v[64:67], v[174:177], v[220:223], v[64:67]
	v_mfma_f32_16x16x32_bf16 v[108:111], v[170:173], v[200:203], v[108:111]
	v_mfma_f32_16x16x32_bf16 v[104:107], v[192:195], v[200:203], v[104:107]
	v_mfma_f32_16x16x32_bf16 v[92:95], v[170:173], v[208:211], v[92:95]
	v_mfma_f32_16x16x32_bf16 v[88:91], v[192:195], v[208:211], v[88:91]
	v_mfma_f32_16x16x32_bf16 v[76:79], v[170:173], v[216:219], v[76:79]
	v_mfma_f32_16x16x32_bf16 v[72:75], v[192:195], v[216:219], v[72:75]
	v_mfma_f32_16x16x32_bf16 v[68:71], v[170:173], v[224:227], v[68:71]
	v_mfma_f32_16x16x32_bf16 v[64:67], v[192:195], v[224:227], v[64:67]
	s_setprio 0
	s_barrier
	s_mov_b32 m0, s42
	v_lshl_add_u64 v[180:181], v[180:181], 0, s[10:11]
	ds_read_b128 v[196:199], v190 offset:49152
	ds_read_b128 v[200:203], v190 offset:50176
	ds_read_b128 v[204:207], v190 offset:51200
	ds_read_b128 v[208:211], v190 offset:52224
	ds_read_b128 v[212:215], v190 offset:53248
	ds_read_b128 v[216:219], v190 offset:54272
	ds_read_b128 v[220:223], v190 offset:55296
	ds_read_b128 v[224:227], v190 offset:56320
	global_load_lds_dwordx4 v[180:181], off
	v_lshl_add_u64 v[180:181], v[228:229], 0, s[10:11]
	s_mov_b32 m0, s43
	s_add_u32 s28, s28, 0x40080
	global_load_lds_dwordx4 v[180:181], off
	s_addc_u32 s29, s29, 0
	s_mov_b32 m0, s48
	v_lshl_add_u64 v[180:181], v[230:231], 0, s[10:11]
	global_load_lds_dwordx4 v146, s[28:29]
	s_mov_b32 m0, s49
	s_nop 0
	global_load_lds_dwordx4 v150, s[28:29]
	s_waitcnt vmcnt(6)
	s_waitcnt lgkmcnt(0)
	s_barrier
	s_setprio 1
	s_waitcnt lgkmcnt(0)
	v_mfma_f32_16x16x32_bf16 v[60:63], v[128:131], v[196:199], v[60:63]
	v_mfma_f32_16x16x32_bf16 v[56:59], v[136:139], v[196:199], v[56:59]
	s_mov_b32 m0, s44
	v_mfma_f32_16x16x32_bf16 v[52:55], v[128:131], v[204:207], v[52:55]
	global_load_lds_dwordx4 v[180:181], off
	v_mfma_f32_16x16x32_bf16 v[48:51], v[136:139], v[204:207], v[48:51]
	v_mfma_f32_16x16x32_bf16 v[36:39], v[128:131], v[212:215], v[36:39]
	v_mfma_f32_16x16x32_bf16 v[32:35], v[136:139], v[212:215], v[32:35]
	v_mfma_f32_16x16x32_bf16 v[20:23], v[128:131], v[220:223], v[20:23]
	v_mfma_f32_16x16x32_bf16 v[16:19], v[136:139], v[220:223], v[16:19]
	v_mfma_f32_16x16x32_bf16 v[60:63], v[132:135], v[200:203], v[60:63]
	v_mfma_f32_16x16x32_bf16 v[56:59], v[140:143], v[200:203], v[56:59]
	v_mfma_f32_16x16x32_bf16 v[52:55], v[132:135], v[208:211], v[52:55]
	v_mfma_f32_16x16x32_bf16 v[48:51], v[140:143], v[208:211], v[48:51]
	v_mfma_f32_16x16x32_bf16 v[36:39], v[132:135], v[216:219], v[36:39]
	v_mfma_f32_16x16x32_bf16 v[32:35], v[140:143], v[216:219], v[32:35]
	v_mfma_f32_16x16x32_bf16 v[20:23], v[132:135], v[224:227], v[20:23]
	v_mfma_f32_16x16x32_bf16 v[16:19], v[140:143], v[224:227], v[16:19]
	v_lshl_add_u64 v[180:181], v[232:233], 0, s[10:11]
	s_mov_b32 m0, s45
	s_setprio 0
	s_setprio 1
	v_mfma_f32_16x16x32_bf16 v[44:47], v[166:169], v[196:199], v[44:47]
	global_load_lds_dwordx4 v[180:181], off
	v_mfma_f32_16x16x32_bf16 v[40:43], v[174:177], v[196:199], v[40:43]
	v_mfma_f32_16x16x32_bf16 v[28:31], v[166:169], v[204:207], v[28:31]
	v_mfma_f32_16x16x32_bf16 v[24:27], v[174:177], v[204:207], v[24:27]
	v_mfma_f32_16x16x32_bf16 v[12:15], v[166:169], v[212:215], v[12:15]
	v_mfma_f32_16x16x32_bf16 v[8:11], v[174:177], v[212:215], v[8:11]
	v_mfma_f32_16x16x32_bf16 v[4:7], v[166:169], v[220:223], v[4:7]
	v_mfma_f32_16x16x32_bf16 v[0:3], v[174:177], v[220:223], v[0:3]
	v_mfma_f32_16x16x32_bf16 v[44:47], v[170:173], v[200:203], v[44:47]
	v_mfma_f32_16x16x32_bf16 v[40:43], v[192:195], v[200:203], v[40:43]
	v_mfma_f32_16x16x32_bf16 v[28:31], v[170:173], v[208:211], v[28:31]
	v_mfma_f32_16x16x32_bf16 v[24:27], v[192:195], v[208:211], v[24:27]
	v_mfma_f32_16x16x32_bf16 v[12:15], v[170:173], v[216:219], v[12:15]
	v_mfma_f32_16x16x32_bf16 v[8:11], v[192:195], v[216:219], v[8:11]
	v_mfma_f32_16x16x32_bf16 v[4:7], v[170:173], v[224:227], v[4:7]
	v_mfma_f32_16x16x32_bf16 v[0:3], v[192:195], v[224:227], v[0:3]
	s_setprio 0
	s_barrier
	s_add_i32 s53, s53, 2
	s_add_u32 s26, s26, 0x100
	s_addc_u32 s27, s27, 0
	s_add_u32 s51, s51, 0x100
	s_addc_u32 s52, s52, 0
	s_cmp_gt_u32 s53, 13
	s_cbranch_scc0 .LBB0_166
	s_and_b64 vcc, exec, s[12:13]
	s_cbranch_vccz .LBB0_169
	s_barrier

.LBB0_206:
	ds_read_b128 v[144:147], v142
	ds_read_b128 v[148:151], v142 offset:1024
	ds_read_b128 v[152:155], v142 offset:2048
	ds_read_b128 v[156:159], v142 offset:3072
	ds_read_b128 v[164:167], v142 offset:16384
	ds_read_b128 v[168:171], v142 offset:17408
	ds_read_b128 v[172:175], v142 offset:18432
	ds_read_b128 v[176:179], v142 offset:19456
	s_add_u32 s23, s26, 0xfffc0080
	s_addc_u32 s28, s27, -1
	s_cmp_eq_u32 s53, 12
	s_cselect_b32 s31, s15, s28
	s_cselect_b32 s30, s49, s23
	s_cselect_b32 s29, s13, s52
	s_cselect_b32 s28, s50, s51
	s_add_i32 m0, s3, 0xc000
	ds_read_b128 v[180:183], v143
	ds_read_b128 v[186:189], v143 offset:1024
	ds_read_b128 v[190:193], v143 offset:2048
	ds_read_b128 v[194:197], v143 offset:3072
	ds_read_b128 v[198:201], v143 offset:4096
	ds_read_b128 v[202:205], v143 offset:5120
	ds_read_b128 v[206:209], v143 offset:6144
	ds_read_b128 v[210:213], v143 offset:7168
	global_load_lds_dwordx4 v128, s[26:27]
	s_add_i32 m0, s3, 0xe000
	v_mov_b32_e32 v131, v129
	global_load_lds_dwordx4 v130, s[26:27]
	s_waitcnt vmcnt(8)
	s_waitcnt lgkmcnt(0)
	s_barrier
	s_setprio 1
	s_waitcnt lgkmcnt(0)
	v_mfma_f32_16x16x32_bf16 v[124:127], v[144:147], v[180:183], v[124:127]
	v_mfma_f32_16x16x32_bf16 v[120:123], v[152:155], v[180:183], v[120:123]
	v_mfma_f32_16x16x32_bf16 v[116:119], v[144:147], v[190:193], v[116:119]
	v_mfma_f32_16x16x32_bf16 v[112:115], v[152:155], v[190:193], v[112:115]
	v_mfma_f32_16x16x32_bf16 v[100:103], v[144:147], v[198:201], v[100:103]
	v_mfma_f32_16x16x32_bf16 v[96:99], v[152:155], v[198:201], v[96:99]
	v_mfma_f32_16x16x32_bf16 v[84:87], v[144:147], v[206:209], v[84:87]
	v_mfma_f32_16x16x32_bf16 v[80:83], v[152:155], v[206:209], v[80:83]
	v_mfma_f32_16x16x32_bf16 v[124:127], v[148:151], v[186:189], v[124:127]
	v_mfma_f32_16x16x32_bf16 v[120:123], v[156:159], v[186:189], v[120:123]
	v_mfma_f32_16x16x32_bf16 v[116:119], v[148:151], v[194:197], v[116:119]
	v_mfma_f32_16x16x32_bf16 v[112:115], v[156:159], v[194:197], v[112:115]
	v_mfma_f32_16x16x32_bf16 v[100:103], v[148:151], v[202:205], v[100:103]
	v_mfma_f32_16x16x32_bf16 v[96:99], v[156:159], v[202:205], v[96:99]
	v_mfma_f32_16x16x32_bf16 v[84:87], v[148:151], v[210:213], v[84:87]
	v_mfma_f32_16x16x32_bf16 v[80:83], v[156:159], v[210:213], v[80:83]
	s_setprio 0
	s_setprio 1
	v_mfma_f32_16x16x32_bf16 v[108:111], v[164:167], v[180:183], v[108:111]
	v_mfma_f32_16x16x32_bf16 v[104:107], v[172:175], v[180:183], v[104:107]
	v_mfma_f32_16x16x32_bf16 v[92:95], v[164:167], v[190:193], v[92:95]
	v_mfma_f32_16x16x32_bf16 v[88:91], v[172:175], v[190:193], v[88:91]
	v_mfma_f32_16x16x32_bf16 v[76:79], v[164:167], v[198:201], v[76:79]
	v_mfma_f32_16x16x32_bf16 v[72:75], v[172:175], v[198:201], v[72:75]
	v_mfma_f32_16x16x32_bf16 v[68:71], v[164:167], v[206:209], v[68:71]
	v_mfma_f32_16x16x32_bf16 v[64:67], v[172:175], v[206:209], v[64:67]
	v_mfma_f32_16x16x32_bf16 v[108:111], v[168:171], v[186:189], v[108:111]
	v_mfma_f32_16x16x32_bf16 v[104:107], v[176:179], v[186:189], v[104:107]
	v_mfma_f32_16x16x32_bf16 v[92:95], v[168:171], v[194:197], v[92:95]
	v_mfma_f32_16x16x32_bf16 v[88:91], v[176:179], v[194:197], v[88:91]
	v_mfma_f32_16x16x32_bf16 v[76:79], v[168:171], v[202:205], v[76:79]
	v_mfma_f32_16x16x32_bf16 v[72:75], v[176:179], v[202:205], v[72:75]
	v_mfma_f32_16x16x32_bf16 v[68:71], v[168:171], v[210:213], v[68:71]
	v_mfma_f32_16x16x32_bf16 v[64:67], v[176:179], v[210:213], v[64:67]
	s_setprio 0
	s_barrier
	s_mov_b32 m0, s17
	ds_read_b128 v[180:183], v143 offset:16384
	ds_read_b128 v[186:189], v143 offset:17408
	ds_read_b128 v[190:193], v143 offset:18432
	ds_read_b128 v[194:197], v143 offset:19456
	ds_read_b128 v[198:201], v143 offset:20480
	ds_read_b128 v[202:205], v143 offset:21504
	ds_read_b128 v[206:209], v143 offset:22528
	ds_read_b128 v[210:213], v143 offset:23552
	global_load_lds_dwordx4 v138, s[28:29]
	s_mov_b32 m0, s22
	s_add_u32 s54, s28, 0x40000
	global_load_lds_dwordx4 v132, s[28:29]
	s_addc_u32 s55, s29, 0
	s_mov_b32 m0, s34
	v_mov_b32_e32 v139, v129
	global_load_lds_dwordx4 v138, s[54:55]
	s_mov_b32 m0, s35
	v_mov_b32_e32 v133, v129
	global_load_lds_dwordx4 v132, s[54:55]
	s_waitcnt vmcnt(6)
	s_waitcnt lgkmcnt(0)
	s_barrier
	s_setprio 1
	s_waitcnt lgkmcnt(0)
	v_mfma_f32_16x16x32_bf16 v[60:63], v[144:147], v[180:183], v[60:63]
	v_mfma_f32_16x16x32_bf16 v[56:59], v[152:155], v[180:183], v[56:59]
	s_mov_b32 m0, s3
	v_lshl_add_u64 v[214:215], s[28:29], 0, v[138:139]
	v_mfma_f32_16x16x32_bf16 v[52:55], v[144:147], v[190:193], v[52:55]
	global_load_lds_dwordx4 v128, s[30:31]
	v_mfma_f32_16x16x32_bf16 v[48:51], v[152:155], v[190:193], v[48:51]
	v_mfma_f32_16x16x32_bf16 v[36:39], v[144:147], v[198:201], v[36:39]
	v_mfma_f32_16x16x32_bf16 v[32:35], v[152:155], v[198:201], v[32:35]
	v_mfma_f32_16x16x32_bf16 v[20:23], v[144:147], v[206:209], v[20:23]
	v_mfma_f32_16x16x32_bf16 v[16:19], v[152:155], v[206:209], v[16:19]
	v_mfma_f32_16x16x32_bf16 v[60:63], v[148:151], v[186:189], v[60:63]
	v_mfma_f32_16x16x32_bf16 v[56:59], v[156:159], v[186:189], v[56:59]
	v_mfma_f32_16x16x32_bf16 v[52:55], v[148:151], v[194:197], v[52:55]
	v_mfma_f32_16x16x32_bf16 v[48:51], v[156:159], v[194:197], v[48:51]
	v_mfma_f32_16x16x32_bf16 v[36:39], v[148:151], v[202:205], v[36:39]
	v_mfma_f32_16x16x32_bf16 v[32:35], v[156:159], v[202:205], v[32:35]
	v_mfma_f32_16x16x32_bf16 v[20:23], v[148:151], v[210:213], v[20:23]
	v_mfma_f32_16x16x32_bf16 v[16:19], v[156:159], v[210:213], v[16:19]
	s_mov_b32 m0, s36
	v_lshl_add_u64 v[216:217], s[28:29], 0, v[132:133]
	s_setprio 0
	s_setprio 1
	v_mfma_f32_16x16x32_bf16 v[44:47], v[164:167], v[180:183], v[44:47]
	global_load_lds_dwordx4 v130, s[30:31]
	v_lshl_add_u64 v[218:219], s[30:31], 0, v[128:129]
	v_lshl_add_u64 v[220:221], s[30:31], 0, v[130:131]
	v_mfma_f32_16x16x32_bf16 v[40:43], v[172:175], v[180:183], v[40:43]
	v_mfma_f32_16x16x32_bf16 v[28:31], v[164:167], v[190:193], v[28:31]
	v_mfma_f32_16x16x32_bf16 v[24:27], v[172:175], v[190:193], v[24:27]
	v_mfma_f32_16x16x32_bf16 v[12:15], v[164:167], v[198:201], v[12:15]
	v_mfma_f32_16x16x32_bf16 v[8:11], v[172:175], v[198:201], v[8:11]
	v_mfma_f32_16x16x32_bf16 v[4:7], v[164:167], v[206:209], v[4:7]
	v_mfma_f32_16x16x32_bf16 v[0:3], v[172:175], v[206:209], v[0:3]
	v_mfma_f32_16x16x32_bf16 v[44:47], v[168:171], v[186:189], v[44:47]
	v_mfma_f32_16x16x32_bf16 v[40:43], v[176:179], v[186:189], v[40:43]
	v_mfma_f32_16x16x32_bf16 v[28:31], v[168:171], v[194:197], v[28:31]
	v_mfma_f32_16x16x32_bf16 v[24:27], v[176:179], v[194:197], v[24:27]
	v_mfma_f32_16x16x32_bf16 v[12:15], v[168:171], v[202:205], v[12:15]
	v_mfma_f32_16x16x32_bf16 v[8:11], v[176:179], v[202:205], v[8:11]
	v_mfma_f32_16x16x32_bf16 v[4:7], v[168:171], v[210:213], v[4:7]
	v_mfma_f32_16x16x32_bf16 v[0:3], v[176:179], v[210:213], v[0:3]
	s_setprio 0
	s_barrier
	ds_read_b128 v[144:147], v142 offset:32768
	ds_read_b128 v[148:151], v142 offset:33792
	ds_read_b128 v[152:155], v142 offset:34816
	ds_read_b128 v[156:159], v142 offset:35840
	ds_read_b128 v[164:167], v142 offset:49152
	ds_read_b128 v[168:171], v142 offset:50176
	ds_read_b128 v[172:175], v142 offset:51200
	ds_read_b128 v[176:179], v142 offset:52224
	s_add_u32 s30, s30, 0x40000
	s_addc_u32 s31, s31, 0
	s_mov_b32 m0, s37
	ds_read_b128 v[180:183], v143 offset:32768
	ds_read_b128 v[186:189], v143 offset:33792
	ds_read_b128 v[190:193], v143 offset:34816
	ds_read_b128 v[194:197], v143 offset:35840
	ds_read_b128 v[198:201], v143 offset:36864
	ds_read_b128 v[202:205], v143 offset:37888
	ds_read_b128 v[206:209], v143 offset:38912
	ds_read_b128 v[210:213], v143 offset:39936
	global_load_lds_dwordx4 v128, s[30:31]
	s_mov_b32 m0, s38
	s_nop 0
	global_load_lds_dwordx4 v130, s[30:31]
	s_waitcnt vmcnt(8)
	s_waitcnt lgkmcnt(0)
	s_barrier
	s_setprio 1
	s_waitcnt lgkmcnt(0)
	v_mfma_f32_16x16x32_bf16 v[124:127], v[144:147], v[180:183], v[124:127]
	v_mfma_f32_16x16x32_bf16 v[120:123], v[152:155], v[180:183], v[120:123]
	v_mfma_f32_16x16x32_bf16 v[116:119], v[144:147], v[190:193], v[116:119]
	v_mfma_f32_16x16x32_bf16 v[112:115], v[152:155], v[190:193], v[112:115]
	v_mfma_f32_16x16x32_bf16 v[100:103], v[144:147], v[198:201], v[100:103]
	v_mfma_f32_16x16x32_bf16 v[96:99], v[152:155], v[198:201], v[96:99]
	v_mfma_f32_16x16x32_bf16 v[84:87], v[144:147], v[206:209], v[84:87]
	v_mfma_f32_16x16x32_bf16 v[80:83], v[152:155], v[206:209], v[80:83]
	v_mfma_f32_16x16x32_bf16 v[124:127], v[148:151], v[186:189], v[124:127]
	v_mfma_f32_16x16x32_bf16 v[120:123], v[156:159], v[186:189], v[120:123]
	v_mfma_f32_16x16x32_bf16 v[116:119], v[148:151], v[194:197], v[116:119]
	v_mfma_f32_16x16x32_bf16 v[112:115], v[156:159], v[194:197], v[112:115]
	v_mfma_f32_16x16x32_bf16 v[100:103], v[148:151], v[202:205], v[100:103]
	v_mfma_f32_16x16x32_bf16 v[96:99], v[156:159], v[202:205], v[96:99]
	v_mfma_f32_16x16x32_bf16 v[84:87], v[148:151], v[210:213], v[84:87]
	v_mfma_f32_16x16x32_bf16 v[80:83], v[156:159], v[210:213], v[80:83]
	s_setprio 0
	s_setprio 1
	v_mfma_f32_16x16x32_bf16 v[108:111], v[164:167], v[180:183], v[108:111]
	v_mfma_f32_16x16x32_bf16 v[104:107], v[172:175], v[180:183], v[104:107]
	v_mfma_f32_16x16x32_bf16 v[92:95], v[164:167], v[190:193], v[92:95]
	v_mfma_f32_16x16x32_bf16 v[88:91], v[172:175], v[190:193], v[88:91]
	v_mfma_f32_16x16x32_bf16 v[76:79], v[164:167], v[198:201], v[76:79]
	v_mfma_f32_16x16x32_bf16 v[72:75], v[172:175], v[198:201], v[72:75]
	v_mfma_f32_16x16x32_bf16 v[68:71], v[164:167], v[206:209], v[68:71]
	v_mfma_f32_16x16x32_bf16 v[64:67], v[172:175], v[206:209], v[64:67]
	v_mfma_f32_16x16x32_bf16 v[108:111], v[168:171], v[186:189], v[108:111]
	v_mfma_f32_16x16x32_bf16 v[104:107], v[176:179], v[186:189], v[104:107]
	v_mfma_f32_16x16x32_bf16 v[92:95], v[168:171], v[194:197], v[92:95]
	v_mfma_f32_16x16x32_bf16 v[88:91], v[176:179], v[194:197], v[88:91]
	v_mfma_f32_16x16x32_bf16 v[76:79], v[168:171], v[202:205], v[76:79]
	v_mfma_f32_16x16x32_bf16 v[72:75], v[176:179], v[202:205], v[72:75]
	v_mfma_f32_16x16x32_bf16 v[68:71], v[168:171], v[210:213], v[68:71]
	v_mfma_f32_16x16x32_bf16 v[64:67], v[176:179], v[210:213], v[64:67]
	s_setprio 0
	s_barrier
	s_mov_b32 m0, s40
	v_lshl_add_u64 v[214:215], v[214:215], 0, s[6:7]
	ds_read_b128 v[180:183], v143 offset:49152
	ds_read_b128 v[186:189], v143 offset:50176
	ds_read_b128 v[190:193], v143 offset:51200
	ds_read_b128 v[194:197], v143 offset:52224
	ds_read_b128 v[198:201], v143 offset:53248
	ds_read_b128 v[202:205], v143 offset:54272
	ds_read_b128 v[206:209], v143 offset:55296
	ds_read_b128 v[210:213], v143 offset:56320
	global_load_lds_dwordx4 v[214:215], off
	v_lshl_add_u64 v[214:215], v[216:217], 0, s[6:7]
	s_mov_b32 m0, s41
	s_add_u32 s28, s28, 0x40080
	global_load_lds_dwordx4 v[214:215], off
	s_addc_u32 s29, s29, 0
	s_mov_b32 m0, s44
	v_lshl_add_u64 v[214:215], v[218:219], 0, s[6:7]
	global_load_lds_dwordx4 v138, s[28:29]
	s_mov_b32 m0, s45
	s_nop 0
	global_load_lds_dwordx4 v132, s[28:29]
	s_waitcnt vmcnt(6)
	s_waitcnt lgkmcnt(0)
	s_barrier
	s_setprio 1
	s_waitcnt lgkmcnt(0)
	v_mfma_f32_16x16x32_bf16 v[60:63], v[144:147], v[180:183], v[60:63]
	v_mfma_f32_16x16x32_bf16 v[56:59], v[152:155], v[180:183], v[56:59]
	s_mov_b32 m0, s42
	v_mfma_f32_16x16x32_bf16 v[52:55], v[144:147], v[190:193], v[52:55]
	global_load_lds_dwordx4 v[214:215], off
	v_mfma_f32_16x16x32_bf16 v[48:51], v[152:155], v[190:193], v[48:51]
	v_mfma_f32_16x16x32_bf16 v[36:39], v[144:147], v[198:201], v[36:39]
	v_mfma_f32_16x16x32_bf16 v[32:35], v[152:155], v[198:201], v[32:35]
	v_mfma_f32_16x16x32_bf16 v[20:23], v[144:147], v[206:209], v[20:23]
	v_mfma_f32_16x16x32_bf16 v[16:19], v[152:155], v[206:209], v[16:19]
	v_mfma_f32_16x16x32_bf16 v[60:63], v[148:151], v[186:189], v[60:63]
	v_mfma_f32_16x16x32_bf16 v[56:59], v[156:159], v[186:189], v[56:59]
	v_mfma_f32_16x16x32_bf16 v[52:55], v[148:151], v[194:197], v[52:55]
	v_mfma_f32_16x16x32_bf16 v[48:51], v[156:159], v[194:197], v[48:51]
	v_mfma_f32_16x16x32_bf16 v[36:39], v[148:151], v[202:205], v[36:39]
	v_mfma_f32_16x16x32_bf16 v[32:35], v[156:159], v[202:205], v[32:35]
	v_mfma_f32_16x16x32_bf16 v[20:23], v[148:151], v[210:213], v[20:23]
	v_mfma_f32_16x16x32_bf16 v[16:19], v[156:159], v[210:213], v[16:19]
	v_lshl_add_u64 v[214:215], v[220:221], 0, s[6:7]
	s_mov_b32 m0, s43
	s_setprio 0
	s_setprio 1
	v_mfma_f32_16x16x32_bf16 v[44:47], v[164:167], v[180:183], v[44:47]
	global_load_lds_dwordx4 v[214:215], off
	v_mfma_f32_16x16x32_bf16 v[40:43], v[172:175], v[180:183], v[40:43]
	v_mfma_f32_16x16x32_bf16 v[28:31], v[164:167], v[190:193], v[28:31]
	v_mfma_f32_16x16x32_bf16 v[24:27], v[172:175], v[190:193], v[24:27]
	v_mfma_f32_16x16x32_bf16 v[12:15], v[164:167], v[198:201], v[12:15]
	v_mfma_f32_16x16x32_bf16 v[8:11], v[172:175], v[198:201], v[8:11]
	v_mfma_f32_16x16x32_bf16 v[4:7], v[164:167], v[206:209], v[4:7]
	v_mfma_f32_16x16x32_bf16 v[0:3], v[172:175], v[206:209], v[0:3]
	v_mfma_f32_16x16x32_bf16 v[44:47], v[168:171], v[186:189], v[44:47]
	v_mfma_f32_16x16x32_bf16 v[40:43], v[176:179], v[186:189], v[40:43]
	v_mfma_f32_16x16x32_bf16 v[28:31], v[168:171], v[194:197], v[28:31]
	v_mfma_f32_16x16x32_bf16 v[24:27], v[176:179], v[194:197], v[24:27]
	v_mfma_f32_16x16x32_bf16 v[12:15], v[168:171], v[202:205], v[12:15]
	v_mfma_f32_16x16x32_bf16 v[8:11], v[176:179], v[202:205], v[8:11]
	v_mfma_f32_16x16x32_bf16 v[4:7], v[168:171], v[210:213], v[4:7]
	v_mfma_f32_16x16x32_bf16 v[0:3], v[176:179], v[210:213], v[0:3]
	s_setprio 0
	s_barrier
	s_add_i32 s53, s53, 2
	s_add_u32 s26, s26, 0x100
	s_addc_u32 s27, s27, 0
	s_add_u32 s51, s51, 0x100
	s_addc_u32 s52, s52, 0
	s_cmp_gt_u32 s53, 13
	s_cbranch_scc0 .LBB0_206
	s_and_b64 vcc, exec, s[8:9]
	s_cbranch_vccz .LBB0_209
	s_barrier

.LBB0_459:
	ds_read_b128 v[144:147], v142
	ds_read_b128 v[148:151], v142 offset:1024
	ds_read_b128 v[152:155], v142 offset:2048
	ds_read_b128 v[156:159], v142 offset:3072
	ds_read_b128 v[164:167], v142 offset:16384
	ds_read_b128 v[168:171], v142 offset:17408
	ds_read_b128 v[172:175], v142 offset:18432
	ds_read_b128 v[176:179], v142 offset:19456
	s_add_u32 s23, s26, 0xfff80080
	s_addc_u32 s28, s27, -1
	s_cmp_eq_u32 s54, 28
	s_cselect_b32 s31, s13, s28
	s_cselect_b32 s30, s50, s23
	s_cselect_b32 s29, s11, s53
	s_cselect_b32 s28, s51, s52
	s_add_i32 m0, s15, 0xc000
	ds_read_b128 v[180:183], v143
	ds_read_b128 v[188:191], v143 offset:1024
	ds_read_b128 v[192:195], v143 offset:2048
	ds_read_b128 v[196:199], v143 offset:3072
	ds_read_b128 v[200:203], v143 offset:4096
	ds_read_b128 v[204:207], v143 offset:5120
	ds_read_b128 v[208:211], v143 offset:6144
	ds_read_b128 v[212:215], v143 offset:7168
	global_load_lds_dwordx4 v128, s[26:27]
	s_add_i32 m0, s15, 0xe000
	v_mov_b32_e32 v131, v129
	global_load_lds_dwordx4 v130, s[26:27]
	s_waitcnt vmcnt(8)
	s_waitcnt lgkmcnt(0)
	s_barrier
	s_setprio 1
	s_waitcnt lgkmcnt(0)
	v_mfma_f32_16x16x32_bf16 v[124:127], v[144:147], v[180:183], v[124:127]
	v_mfma_f32_16x16x32_bf16 v[120:123], v[152:155], v[180:183], v[120:123]
	v_mfma_f32_16x16x32_bf16 v[116:119], v[144:147], v[192:195], v[116:119]
	v_mfma_f32_16x16x32_bf16 v[112:115], v[152:155], v[192:195], v[112:115]
	v_mfma_f32_16x16x32_bf16 v[100:103], v[144:147], v[200:203], v[100:103]
	v_mfma_f32_16x16x32_bf16 v[96:99], v[152:155], v[200:203], v[96:99]
	v_mfma_f32_16x16x32_bf16 v[84:87], v[144:147], v[208:211], v[84:87]
	v_mfma_f32_16x16x32_bf16 v[80:83], v[152:155], v[208:211], v[80:83]
	v_mfma_f32_16x16x32_bf16 v[124:127], v[148:151], v[188:191], v[124:127]
	v_mfma_f32_16x16x32_bf16 v[120:123], v[156:159], v[188:191], v[120:123]
	v_mfma_f32_16x16x32_bf16 v[116:119], v[148:151], v[196:199], v[116:119]
	v_mfma_f32_16x16x32_bf16 v[112:115], v[156:159], v[196:199], v[112:115]
	v_mfma_f32_16x16x32_bf16 v[100:103], v[148:151], v[204:207], v[100:103]
	v_mfma_f32_16x16x32_bf16 v[96:99], v[156:159], v[204:207], v[96:99]
	v_mfma_f32_16x16x32_bf16 v[84:87], v[148:151], v[212:215], v[84:87]
	v_mfma_f32_16x16x32_bf16 v[80:83], v[156:159], v[212:215], v[80:83]
	s_setprio 0
	s_setprio 1
	v_mfma_f32_16x16x32_bf16 v[108:111], v[164:167], v[180:183], v[108:111]
	v_mfma_f32_16x16x32_bf16 v[104:107], v[172:175], v[180:183], v[104:107]
	v_mfma_f32_16x16x32_bf16 v[92:95], v[164:167], v[192:195], v[92:95]
	v_mfma_f32_16x16x32_bf16 v[88:91], v[172:175], v[192:195], v[88:91]
	v_mfma_f32_16x16x32_bf16 v[76:79], v[164:167], v[200:203], v[76:79]
	v_mfma_f32_16x16x32_bf16 v[72:75], v[172:175], v[200:203], v[72:75]
	v_mfma_f32_16x16x32_bf16 v[68:71], v[164:167], v[208:211], v[68:71]
	v_mfma_f32_16x16x32_bf16 v[64:67], v[172:175], v[208:211], v[64:67]
	v_mfma_f32_16x16x32_bf16 v[108:111], v[168:171], v[188:191], v[108:111]
	v_mfma_f32_16x16x32_bf16 v[104:107], v[176:179], v[188:191], v[104:107]
	v_mfma_f32_16x16x32_bf16 v[92:95], v[168:171], v[196:199], v[92:95]
	v_mfma_f32_16x16x32_bf16 v[88:91], v[176:179], v[196:199], v[88:91]
	v_mfma_f32_16x16x32_bf16 v[76:79], v[168:171], v[204:207], v[76:79]
	v_mfma_f32_16x16x32_bf16 v[72:75], v[176:179], v[204:207], v[72:75]
	v_mfma_f32_16x16x32_bf16 v[68:71], v[168:171], v[212:215], v[68:71]
	v_mfma_f32_16x16x32_bf16 v[64:67], v[176:179], v[212:215], v[64:67]
	s_setprio 0
	s_barrier
	s_mov_b32 m0, s34
	ds_read_b128 v[180:183], v143 offset:16384
	ds_read_b128 v[188:191], v143 offset:17408
	ds_read_b128 v[192:195], v143 offset:18432
	ds_read_b128 v[196:199], v143 offset:19456
	ds_read_b128 v[200:203], v143 offset:20480
	ds_read_b128 v[204:207], v143 offset:21504
	ds_read_b128 v[208:211], v143 offset:22528
	ds_read_b128 v[212:215], v143 offset:23552
	global_load_lds_dwordx4 v138, s[28:29]
	s_mov_b32 m0, s35
	s_add_u32 s86, s28, 0x80000
	global_load_lds_dwordx4 v132, s[28:29]
	s_addc_u32 s87, s29, 0
	s_mov_b32 m0, s36
	v_mov_b32_e32 v139, v129
	global_load_lds_dwordx4 v138, s[86:87]
	s_mov_b32 m0, s37
	v_mov_b32_e32 v133, v129
	global_load_lds_dwordx4 v132, s[86:87]
	s_waitcnt vmcnt(6)
	s_waitcnt lgkmcnt(0)
	s_barrier
	s_setprio 1
	s_waitcnt lgkmcnt(0)
	v_mfma_f32_16x16x32_bf16 v[60:63], v[144:147], v[180:183], v[60:63]
	v_mfma_f32_16x16x32_bf16 v[56:59], v[152:155], v[180:183], v[56:59]
	s_mov_b32 m0, s15
	v_lshl_add_u64 v[216:217], s[28:29], 0, v[138:139]
	v_mfma_f32_16x16x32_bf16 v[52:55], v[144:147], v[192:195], v[52:55]
	global_load_lds_dwordx4 v128, s[30:31]
	v_mfma_f32_16x16x32_bf16 v[48:51], v[152:155], v[192:195], v[48:51]
	v_mfma_f32_16x16x32_bf16 v[36:39], v[144:147], v[200:203], v[36:39]
	v_mfma_f32_16x16x32_bf16 v[32:35], v[152:155], v[200:203], v[32:35]
	v_mfma_f32_16x16x32_bf16 v[20:23], v[144:147], v[208:211], v[20:23]
	v_mfma_f32_16x16x32_bf16 v[16:19], v[152:155], v[208:211], v[16:19]
	v_mfma_f32_16x16x32_bf16 v[60:63], v[148:151], v[188:191], v[60:63]
	v_mfma_f32_16x16x32_bf16 v[56:59], v[156:159], v[188:191], v[56:59]
	v_mfma_f32_16x16x32_bf16 v[52:55], v[148:151], v[196:199], v[52:55]
	v_mfma_f32_16x16x32_bf16 v[48:51], v[156:159], v[196:199], v[48:51]
	v_mfma_f32_16x16x32_bf16 v[36:39], v[148:151], v[204:207], v[36:39]
	v_mfma_f32_16x16x32_bf16 v[32:35], v[156:159], v[204:207], v[32:35]
	v_mfma_f32_16x16x32_bf16 v[20:23], v[148:151], v[212:215], v[20:23]
	v_mfma_f32_16x16x32_bf16 v[16:19], v[156:159], v[212:215], v[16:19]
	s_mov_b32 m0, s38
	v_lshl_add_u64 v[218:219], s[28:29], 0, v[132:133]
	s_setprio 0
	s_setprio 1
	v_mfma_f32_16x16x32_bf16 v[44:47], v[164:167], v[180:183], v[44:47]
	global_load_lds_dwordx4 v130, s[30:31]
	v_lshl_add_u64 v[220:221], s[30:31], 0, v[128:129]
	v_lshl_add_u64 v[222:223], s[30:31], 0, v[130:131]
	v_mfma_f32_16x16x32_bf16 v[40:43], v[172:175], v[180:183], v[40:43]
	v_mfma_f32_16x16x32_bf16 v[28:31], v[164:167], v[192:195], v[28:31]
	v_mfma_f32_16x16x32_bf16 v[24:27], v[172:175], v[192:195], v[24:27]
	v_mfma_f32_16x16x32_bf16 v[12:15], v[164:167], v[200:203], v[12:15]
	v_mfma_f32_16x16x32_bf16 v[8:11], v[172:175], v[200:203], v[8:11]
	v_mfma_f32_16x16x32_bf16 v[4:7], v[164:167], v[208:211], v[4:7]
	v_mfma_f32_16x16x32_bf16 v[0:3], v[172:175], v[208:211], v[0:3]
	v_mfma_f32_16x16x32_bf16 v[44:47], v[168:171], v[188:191], v[44:47]
	v_mfma_f32_16x16x32_bf16 v[40:43], v[176:179], v[188:191], v[40:43]
	v_mfma_f32_16x16x32_bf16 v[28:31], v[168:171], v[196:199], v[28:31]
	v_mfma_f32_16x16x32_bf16 v[24:27], v[176:179], v[196:199], v[24:27]
	v_mfma_f32_16x16x32_bf16 v[12:15], v[168:171], v[204:207], v[12:15]
	v_mfma_f32_16x16x32_bf16 v[8:11], v[176:179], v[204:207], v[8:11]
	v_mfma_f32_16x16x32_bf16 v[4:7], v[168:171], v[212:215], v[4:7]
	v_mfma_f32_16x16x32_bf16 v[0:3], v[176:179], v[212:215], v[0:3]
	s_setprio 0
	s_barrier
	ds_read_b128 v[144:147], v142 offset:32768
	ds_read_b128 v[148:151], v142 offset:33792
	ds_read_b128 v[152:155], v142 offset:34816
	ds_read_b128 v[156:159], v142 offset:35840
	ds_read_b128 v[164:167], v142 offset:49152
	ds_read_b128 v[168:171], v142 offset:50176
	ds_read_b128 v[172:175], v142 offset:51200
	ds_read_b128 v[176:179], v142 offset:52224
	s_add_u32 s30, s30, 0x80000
	s_addc_u32 s31, s31, 0
	s_mov_b32 m0, s39
	ds_read_b128 v[180:183], v143 offset:32768
	ds_read_b128 v[188:191], v143 offset:33792
	ds_read_b128 v[192:195], v143 offset:34816
	ds_read_b128 v[196:199], v143 offset:35840
	ds_read_b128 v[200:203], v143 offset:36864
	ds_read_b128 v[204:207], v143 offset:37888
	ds_read_b128 v[208:211], v143 offset:38912
	ds_read_b128 v[212:215], v143 offset:39936
	global_load_lds_dwordx4 v128, s[30:31]
	s_mov_b32 m0, s40
	s_nop 0
	global_load_lds_dwordx4 v130, s[30:31]
	s_waitcnt vmcnt(8)
	s_waitcnt lgkmcnt(0)
	s_barrier
	s_setprio 1
	s_waitcnt lgkmcnt(0)
	v_mfma_f32_16x16x32_bf16 v[124:127], v[144:147], v[180:183], v[124:127]
	v_mfma_f32_16x16x32_bf16 v[120:123], v[152:155], v[180:183], v[120:123]
	v_mfma_f32_16x16x32_bf16 v[116:119], v[144:147], v[192:195], v[116:119]
	v_mfma_f32_16x16x32_bf16 v[112:115], v[152:155], v[192:195], v[112:115]
	v_mfma_f32_16x16x32_bf16 v[100:103], v[144:147], v[200:203], v[100:103]
	v_mfma_f32_16x16x32_bf16 v[96:99], v[152:155], v[200:203], v[96:99]
	v_mfma_f32_16x16x32_bf16 v[84:87], v[144:147], v[208:211], v[84:87]
	v_mfma_f32_16x16x32_bf16 v[80:83], v[152:155], v[208:211], v[80:83]
	v_mfma_f32_16x16x32_bf16 v[124:127], v[148:151], v[188:191], v[124:127]
	v_mfma_f32_16x16x32_bf16 v[120:123], v[156:159], v[188:191], v[120:123]
	v_mfma_f32_16x16x32_bf16 v[116:119], v[148:151], v[196:199], v[116:119]
	v_mfma_f32_16x16x32_bf16 v[112:115], v[156:159], v[196:199], v[112:115]
	v_mfma_f32_16x16x32_bf16 v[100:103], v[148:151], v[204:207], v[100:103]
	v_mfma_f32_16x16x32_bf16 v[96:99], v[156:159], v[204:207], v[96:99]
	v_mfma_f32_16x16x32_bf16 v[84:87], v[148:151], v[212:215], v[84:87]
	v_mfma_f32_16x16x32_bf16 v[80:83], v[156:159], v[212:215], v[80:83]
	s_setprio 0
	s_setprio 1
	v_mfma_f32_16x16x32_bf16 v[108:111], v[164:167], v[180:183], v[108:111]
	v_mfma_f32_16x16x32_bf16 v[104:107], v[172:175], v[180:183], v[104:107]
	v_mfma_f32_16x16x32_bf16 v[92:95], v[164:167], v[192:195], v[92:95]
	v_mfma_f32_16x16x32_bf16 v[88:91], v[172:175], v[192:195], v[88:91]
	v_mfma_f32_16x16x32_bf16 v[76:79], v[164:167], v[200:203], v[76:79]
	v_mfma_f32_16x16x32_bf16 v[72:75], v[172:175], v[200:203], v[72:75]
	v_mfma_f32_16x16x32_bf16 v[68:71], v[164:167], v[208:211], v[68:71]
	v_mfma_f32_16x16x32_bf16 v[64:67], v[172:175], v[208:211], v[64:67]
	v_mfma_f32_16x16x32_bf16 v[108:111], v[168:171], v[188:191], v[108:111]
	v_mfma_f32_16x16x32_bf16 v[104:107], v[176:179], v[188:191], v[104:107]
	v_mfma_f32_16x16x32_bf16 v[92:95], v[168:171], v[196:199], v[92:95]
	v_mfma_f32_16x16x32_bf16 v[88:91], v[176:179], v[196:199], v[88:91]
	v_mfma_f32_16x16x32_bf16 v[76:79], v[168:171], v[204:207], v[76:79]
	v_mfma_f32_16x16x32_bf16 v[72:75], v[176:179], v[204:207], v[72:75]
	v_mfma_f32_16x16x32_bf16 v[68:71], v[168:171], v[212:215], v[68:71]
	v_mfma_f32_16x16x32_bf16 v[64:67], v[176:179], v[212:215], v[64:67]
	s_setprio 0
	s_barrier
	s_mov_b32 m0, s42
	v_lshl_add_u64 v[216:217], v[216:217], 0, s[6:7]
	ds_read_b128 v[180:183], v143 offset:49152
	ds_read_b128 v[188:191], v143 offset:50176
	ds_read_b128 v[192:195], v143 offset:51200
	ds_read_b128 v[196:199], v143 offset:52224
	ds_read_b128 v[200:203], v143 offset:53248
	ds_read_b128 v[204:207], v143 offset:54272
	ds_read_b128 v[208:211], v143 offset:55296
	ds_read_b128 v[212:215], v143 offset:56320
	global_load_lds_dwordx4 v[216:217], off
	v_lshl_add_u64 v[216:217], v[218:219], 0, s[6:7]
	s_mov_b32 m0, s43
	s_add_u32 s28, s28, 0x80080
	global_load_lds_dwordx4 v[216:217], off
	s_addc_u32 s29, s29, 0
	s_mov_b32 m0, s47
	v_lshl_add_u64 v[216:217], v[220:221], 0, s[6:7]
	global_load_lds_dwordx4 v138, s[28:29]
	s_mov_b32 m0, s48
	s_nop 0
	global_load_lds_dwordx4 v132, s[28:29]
	s_waitcnt vmcnt(6)
	s_waitcnt lgkmcnt(0)
	s_barrier
	s_setprio 1
	s_waitcnt lgkmcnt(0)
	v_mfma_f32_16x16x32_bf16 v[60:63], v[144:147], v[180:183], v[60:63]
	v_mfma_f32_16x16x32_bf16 v[56:59], v[152:155], v[180:183], v[56:59]
	s_mov_b32 m0, s44
	v_mfma_f32_16x16x32_bf16 v[52:55], v[144:147], v[192:195], v[52:55]
	global_load_lds_dwordx4 v[216:217], off
	v_mfma_f32_16x16x32_bf16 v[48:51], v[152:155], v[192:195], v[48:51]
	v_mfma_f32_16x16x32_bf16 v[36:39], v[144:147], v[200:203], v[36:39]
	v_mfma_f32_16x16x32_bf16 v[32:35], v[152:155], v[200:203], v[32:35]
	v_mfma_f32_16x16x32_bf16 v[20:23], v[144:147], v[208:211], v[20:23]
	v_mfma_f32_16x16x32_bf16 v[16:19], v[152:155], v[208:211], v[16:19]
	v_mfma_f32_16x16x32_bf16 v[60:63], v[148:151], v[188:191], v[60:63]
	v_mfma_f32_16x16x32_bf16 v[56:59], v[156:159], v[188:191], v[56:59]
	v_mfma_f32_16x16x32_bf16 v[52:55], v[148:151], v[196:199], v[52:55]
	v_mfma_f32_16x16x32_bf16 v[48:51], v[156:159], v[196:199], v[48:51]
	v_mfma_f32_16x16x32_bf16 v[36:39], v[148:151], v[204:207], v[36:39]
	v_mfma_f32_16x16x32_bf16 v[32:35], v[156:159], v[204:207], v[32:35]
	v_mfma_f32_16x16x32_bf16 v[20:23], v[148:151], v[212:215], v[20:23]
	v_mfma_f32_16x16x32_bf16 v[16:19], v[156:159], v[212:215], v[16:19]
	v_lshl_add_u64 v[216:217], v[222:223], 0, s[6:7]
	s_mov_b32 m0, s45
	s_setprio 0
	s_setprio 1
	v_mfma_f32_16x16x32_bf16 v[44:47], v[164:167], v[180:183], v[44:47]
	global_load_lds_dwordx4 v[216:217], off
	v_mfma_f32_16x16x32_bf16 v[40:43], v[172:175], v[180:183], v[40:43]
	v_mfma_f32_16x16x32_bf16 v[28:31], v[164:167], v[192:195], v[28:31]
	v_mfma_f32_16x16x32_bf16 v[24:27], v[172:175], v[192:195], v[24:27]
	v_mfma_f32_16x16x32_bf16 v[12:15], v[164:167], v[200:203], v[12:15]
	v_mfma_f32_16x16x32_bf16 v[8:11], v[172:175], v[200:203], v[8:11]
	v_mfma_f32_16x16x32_bf16 v[4:7], v[164:167], v[208:211], v[4:7]
	v_mfma_f32_16x16x32_bf16 v[0:3], v[172:175], v[208:211], v[0:3]
	v_mfma_f32_16x16x32_bf16 v[44:47], v[168:171], v[188:191], v[44:47]
	v_mfma_f32_16x16x32_bf16 v[40:43], v[176:179], v[188:191], v[40:43]
	v_mfma_f32_16x16x32_bf16 v[28:31], v[168:171], v[196:199], v[28:31]
	v_mfma_f32_16x16x32_bf16 v[24:27], v[176:179], v[196:199], v[24:27]
	v_mfma_f32_16x16x32_bf16 v[12:15], v[168:171], v[204:207], v[12:15]
	v_mfma_f32_16x16x32_bf16 v[8:11], v[176:179], v[204:207], v[8:11]
	v_mfma_f32_16x16x32_bf16 v[4:7], v[168:171], v[212:215], v[4:7]
	v_mfma_f32_16x16x32_bf16 v[0:3], v[176:179], v[212:215], v[0:3]
	s_setprio 0
	s_barrier
	s_add_i32 s54, s54, 2
	s_add_u32 s26, s26, 0x100
	s_addc_u32 s27, s27, 0
	s_add_u32 s52, s52, 0x100
	s_addc_u32 s53, s53, 0
	s_cmp_gt_u32 s54, 29
	s_cbranch_scc0 .LBB0_459
	s_and_b64 vcc, exec, s[8:9]
	s_cbranch_vccz .LBB0_462
	s_barrier

.LBB0_585:
	ds_read_b128 v[24:27], v189
	ds_read_b128 v[28:31], v189 offset:16
	ds_read_b128 v[16:19], v189 offset:2048
	ds_read_b128 v[20:23], v189 offset:2064
	ds_read_b128 v[8:11], v189 offset:16384
	ds_read_b128 v[12:15], v189 offset:16400
	ds_read_b128 v[0:3], v189 offset:18432
	ds_read_b128 v[4:7], v189 offset:18448
	s_add_u32 s23, s30, 0xfffe0080
	s_addc_u32 s34, s31, -1
	s_cmp_eq_u32 s64, 4
	s_cselect_b32 s37, s21, s34
	s_cselect_b32 s36, s53, s23
	s_cselect_b32 s35, s15, s63
	s_cselect_b32 s34, s54, s55
	s_add_i32 m0, s11, 0xc000
	ds_read_b128 v[176:179], v190
	ds_read_b128 v[180:183], v190 offset:16
	ds_read_b128 v[192:195], v190 offset:2048
	ds_read_b128 v[196:199], v190 offset:2064
	ds_read_b128 v[200:203], v190 offset:4096
	ds_read_b128 v[204:207], v190 offset:4112
	ds_read_b128 v[208:211], v190 offset:6144
	ds_read_b128 v[212:215], v190 offset:6160
	global_load_lds_dwordx4 v164, s[30:31]
	s_add_i32 m0, s11, 0xe000
	v_mov_b32_e32 v169, v165
	global_load_lds_dwordx4 v168, s[30:31]
	s_waitcnt vmcnt(8)
	s_waitcnt lgkmcnt(0)
	s_barrier
	s_setprio 1
	s_waitcnt lgkmcnt(0)
	v_mfma_f32_16x16x128_f8f6f4 v[156:159], v[24:31], v[176:183], v[156:159]
	v_mfma_f32_16x16x128_f8f6f4 v[148:151], v[16:23], v[176:183], v[148:151]
	v_mfma_f32_16x16x128_f8f6f4 v[140:143], v[24:31], v[192:199], v[140:143]
	v_mfma_f32_16x16x128_f8f6f4 v[132:135], v[16:23], v[192:199], v[132:135]
	v_mfma_f32_16x16x128_f8f6f4 v[124:127], v[24:31], v[200:207], v[124:127]
	v_mfma_f32_16x16x128_f8f6f4 v[116:119], v[16:23], v[200:207], v[116:119]
	v_mfma_f32_16x16x128_f8f6f4 v[108:111], v[24:31], v[208:215], v[108:111]
	v_mfma_f32_16x16x128_f8f6f4 v[100:103], v[16:23], v[208:215], v[100:103]
	s_setprio 0
	s_setprio 1
	v_mfma_f32_16x16x128_f8f6f4 v[152:155], v[8:15], v[176:183], v[152:155]
	v_mfma_f32_16x16x128_f8f6f4 v[144:147], v[0:7], v[176:183], v[144:147]
	v_mfma_f32_16x16x128_f8f6f4 v[136:139], v[8:15], v[192:199], v[136:139]
	v_mfma_f32_16x16x128_f8f6f4 v[128:131], v[0:7], v[192:199], v[128:131]
	v_mfma_f32_16x16x128_f8f6f4 v[120:123], v[8:15], v[200:207], v[120:123]
	v_mfma_f32_16x16x128_f8f6f4 v[112:115], v[0:7], v[200:207], v[112:115]
	v_mfma_f32_16x16x128_f8f6f4 v[104:107], v[8:15], v[208:215], v[104:107]
	v_mfma_f32_16x16x128_f8f6f4 v[96:99], v[0:7], v[208:215], v[96:99]
	s_setprio 0
	s_barrier
	s_mov_b32 m0, s13
	ds_read_b128 v[192:195], v190 offset:16384
	ds_read_b128 v[196:199], v190 offset:16400
	ds_read_b128 v[200:203], v190 offset:18432
	ds_read_b128 v[204:207], v190 offset:18448
	ds_read_b128 v[208:211], v190 offset:20480
	ds_read_b128 v[212:215], v190 offset:20496
	ds_read_b128 v[216:219], v190 offset:22528
	ds_read_b128 v[220:223], v190 offset:22544
	global_load_lds_dwordx4 v166, s[34:35]
	s_mov_b32 m0, s22
	s_add_u32 s86, s34, 0x20000
	global_load_lds_dwordx4 v170, s[34:35]
	s_addc_u32 s87, s35, 0
	s_mov_b32 m0, s29
	v_mov_b32_e32 v167, v165
	global_load_lds_dwordx4 v166, s[86:87]
	s_mov_b32 m0, s38
	v_mov_b32_e32 v171, v165
	global_load_lds_dwordx4 v170, s[86:87]
	s_waitcnt vmcnt(6)
	s_waitcnt lgkmcnt(0)
	s_barrier
	s_setprio 1
	s_waitcnt lgkmcnt(0)
	v_mfma_f32_16x16x128_f8f6f4 v[92:95], v[24:31], v[192:199], v[92:95]
	v_mfma_f32_16x16x128_f8f6f4 v[84:87], v[16:23], v[192:199], v[84:87]
	s_mov_b32 m0, s11
	v_lshl_add_u64 v[182:183], s[34:35], 0, v[166:167]
	v_mfma_f32_16x16x128_f8f6f4 v[76:79], v[24:31], v[200:207], v[76:79]
	global_load_lds_dwordx4 v164, s[36:37]
	v_mfma_f32_16x16x128_f8f6f4 v[68:71], v[16:23], v[200:207], v[68:71]
	v_mfma_f32_16x16x128_f8f6f4 v[60:63], v[24:31], v[208:215], v[60:63]
	v_mfma_f32_16x16x128_f8f6f4 v[52:55], v[16:23], v[208:215], v[52:55]
	v_mfma_f32_16x16x128_f8f6f4 v[44:47], v[24:31], v[216:223], v[44:47]
	v_mfma_f32_16x16x128_f8f6f4 v[36:39], v[16:23], v[216:223], v[36:39]
	s_mov_b32 m0, s39
	v_lshl_add_u64 v[180:181], s[34:35], 0, v[170:171]
	s_setprio 0
	s_setprio 1
	v_mfma_f32_16x16x128_f8f6f4 v[88:91], v[8:15], v[192:199], v[88:91]
	global_load_lds_dwordx4 v168, s[36:37]
	v_lshl_add_u64 v[178:179], s[36:37], 0, v[164:165]
	v_lshl_add_u64 v[176:177], s[36:37], 0, v[168:169]
	v_mfma_f32_16x16x128_f8f6f4 v[80:83], v[0:7], v[192:199], v[80:83]
	v_mfma_f32_16x16x128_f8f6f4 v[72:75], v[8:15], v[200:207], v[72:75]
	v_mfma_f32_16x16x128_f8f6f4 v[64:67], v[0:7], v[200:207], v[64:67]
	v_mfma_f32_16x16x128_f8f6f4 v[56:59], v[8:15], v[208:215], v[56:59]
	v_mfma_f32_16x16x128_f8f6f4 v[48:51], v[0:7], v[208:215], v[48:51]
	v_mfma_f32_16x16x128_f8f6f4 v[40:43], v[8:15], v[216:223], v[40:43]
	v_mfma_f32_16x16x128_f8f6f4 v[32:35], v[0:7], v[216:223], v[32:35]
	s_setprio 0
	s_barrier
	ds_read_b128 v[0:3], v189 offset:32768
	ds_read_b128 v[4:7], v189 offset:32784
	ds_read_b128 v[8:11], v189 offset:34816
	ds_read_b128 v[12:15], v189 offset:34832
	ds_read_b128 v[16:19], v189 offset:49152
	ds_read_b128 v[20:23], v189 offset:49168
	ds_read_b128 v[24:27], v189 offset:51200
	ds_read_b128 v[28:31], v189 offset:51216
	s_add_u32 s36, s36, 0x20000
	s_addc_u32 s37, s37, 0
	s_mov_b32 m0, s40
	ds_read_b128 v[192:195], v190 offset:32768
	ds_read_b128 v[196:199], v190 offset:32784
	ds_read_b128 v[200:203], v190 offset:34816
	ds_read_b128 v[204:207], v190 offset:34832
	ds_read_b128 v[208:211], v190 offset:36864
	ds_read_b128 v[212:215], v190 offset:36880
	ds_read_b128 v[216:219], v190 offset:38912
	ds_read_b128 v[220:223], v190 offset:38928
	global_load_lds_dwordx4 v164, s[36:37]
	s_mov_b32 m0, s41
	s_nop 0
	global_load_lds_dwordx4 v168, s[36:37]
	s_waitcnt vmcnt(8)
	s_waitcnt lgkmcnt(0)
	s_barrier
	s_setprio 1
	s_waitcnt lgkmcnt(0)
	v_mfma_f32_16x16x128_f8f6f4 v[156:159], v[0:7], v[192:199], v[156:159]
	v_mfma_f32_16x16x128_f8f6f4 v[148:151], v[8:15], v[192:199], v[148:151]
	v_mfma_f32_16x16x128_f8f6f4 v[140:143], v[0:7], v[200:207], v[140:143]
	v_mfma_f32_16x16x128_f8f6f4 v[132:135], v[8:15], v[200:207], v[132:135]
	v_mfma_f32_16x16x128_f8f6f4 v[124:127], v[0:7], v[208:215], v[124:127]
	v_mfma_f32_16x16x128_f8f6f4 v[116:119], v[8:15], v[208:215], v[116:119]
	v_mfma_f32_16x16x128_f8f6f4 v[108:111], v[0:7], v[216:223], v[108:111]
	v_mfma_f32_16x16x128_f8f6f4 v[100:103], v[8:15], v[216:223], v[100:103]
	s_setprio 0
	s_setprio 1
	v_mfma_f32_16x16x128_f8f6f4 v[152:155], v[16:23], v[192:199], v[152:155]
	v_mfma_f32_16x16x128_f8f6f4 v[144:147], v[24:31], v[192:199], v[144:147]
	v_mfma_f32_16x16x128_f8f6f4 v[136:139], v[16:23], v[200:207], v[136:139]
	v_mfma_f32_16x16x128_f8f6f4 v[128:131], v[24:31], v[200:207], v[128:131]
	v_mfma_f32_16x16x128_f8f6f4 v[120:123], v[16:23], v[208:215], v[120:123]
	v_mfma_f32_16x16x128_f8f6f4 v[112:115], v[24:31], v[208:215], v[112:115]
	v_mfma_f32_16x16x128_f8f6f4 v[104:107], v[16:23], v[216:223], v[104:107]
	v_mfma_f32_16x16x128_f8f6f4 v[96:99], v[24:31], v[216:223], v[96:99]
	s_setprio 0
	s_barrier
	s_mov_b32 m0, s43
	v_lshl_add_u64 v[182:183], v[182:183], 0, s[6:7]
	ds_read_b128 v[192:195], v190 offset:49152
	ds_read_b128 v[196:199], v190 offset:49168
	ds_read_b128 v[200:203], v190 offset:51200
	ds_read_b128 v[204:207], v190 offset:51216
	ds_read_b128 v[208:211], v190 offset:53248
	ds_read_b128 v[212:215], v190 offset:53264
	ds_read_b128 v[216:219], v190 offset:55296
	ds_read_b128 v[220:223], v190 offset:55312
	global_load_lds_dwordx4 v[182:183], off
	v_lshl_add_u64 v[180:181], v[180:181], 0, s[6:7]
	s_mov_b32 m0, s44
	s_add_u32 s34, s34, 0x20080
	global_load_lds_dwordx4 v[180:181], off
	s_addc_u32 s35, s35, 0
	s_mov_b32 m0, s48
	v_lshl_add_u64 v[178:179], v[178:179], 0, s[6:7]
	global_load_lds_dwordx4 v166, s[34:35]
	s_mov_b32 m0, s49
	v_lshl_add_u64 v[176:177], v[176:177], 0, s[6:7]
	global_load_lds_dwordx4 v170, s[34:35]
	s_waitcnt vmcnt(6)
	s_waitcnt lgkmcnt(0)
	s_barrier
	s_setprio 1
	s_waitcnt lgkmcnt(0)
	v_mfma_f32_16x16x128_f8f6f4 v[92:95], v[0:7], v[192:199], v[92:95]
	v_mfma_f32_16x16x128_f8f6f4 v[84:87], v[8:15], v[192:199], v[84:87]
	s_mov_b32 m0, s45
	v_mfma_f32_16x16x128_f8f6f4 v[76:79], v[0:7], v[200:207], v[76:79]
	global_load_lds_dwordx4 v[178:179], off
	v_mfma_f32_16x16x128_f8f6f4 v[68:71], v[8:15], v[200:207], v[68:71]
	v_mfma_f32_16x16x128_f8f6f4 v[60:63], v[0:7], v[208:215], v[60:63]
	v_mfma_f32_16x16x128_f8f6f4 v[52:55], v[8:15], v[208:215], v[52:55]
	v_mfma_f32_16x16x128_f8f6f4 v[44:47], v[0:7], v[216:223], v[44:47]
	v_mfma_f32_16x16x128_f8f6f4 v[36:39], v[8:15], v[216:223], v[36:39]
	s_mov_b32 m0, s47
	s_setprio 0
	s_setprio 1
	v_mfma_f32_16x16x128_f8f6f4 v[88:91], v[16:23], v[192:199], v[88:91]
	global_load_lds_dwordx4 v[176:177], off
	v_mfma_f32_16x16x128_f8f6f4 v[80:83], v[24:31], v[192:199], v[80:83]
	v_mfma_f32_16x16x128_f8f6f4 v[72:75], v[16:23], v[200:207], v[72:75]
	v_mfma_f32_16x16x128_f8f6f4 v[64:67], v[24:31], v[200:207], v[64:67]
	v_mfma_f32_16x16x128_f8f6f4 v[56:59], v[16:23], v[208:215], v[56:59]
	v_mfma_f32_16x16x128_f8f6f4 v[48:51], v[24:31], v[208:215], v[48:51]
	v_mfma_f32_16x16x128_f8f6f4 v[40:43], v[16:23], v[216:223], v[40:43]
	v_mfma_f32_16x16x128_f8f6f4 v[32:35], v[24:31], v[216:223], v[32:35]
	s_setprio 0
	s_barrier
	s_add_i32 s64, s64, 2
	s_add_u32 s30, s30, 0x100
	s_addc_u32 s31, s31, 0
	s_add_u32 s55, s55, 0x100
	s_addc_u32 s63, s63, 0
	s_cmp_gt_u32 s64, 5
	s_cbranch_scc0 .LBB0_585
	s_nop 15
	s_nop 15
	s_and_b64 vcc, exec, s[8:9]
	s_cbranch_vccz .LBB0_588
	s_barrier

.LBB0_662:
	ds_read_b128 v[24:27], v189
	ds_read_b128 v[28:31], v189 offset:16
	ds_read_b128 v[16:19], v189 offset:2048
	ds_read_b128 v[20:23], v189 offset:2064
	ds_read_b128 v[8:11], v189 offset:16384
	ds_read_b128 v[12:15], v189 offset:16400
	ds_read_b128 v[0:3], v189 offset:18432
	ds_read_b128 v[4:7], v189 offset:18448
	s_add_u32 s24, s20, 0xfffa8080
	s_addc_u32 s25, s21, -1
	s_cmp_eq_u32 s48, 18
	s_cselect_b32 s27, s1, s25
	s_cselect_b32 s26, s0, s24
	s_cselect_b32 s25, s15, s47
	s_cselect_b32 s24, s14, s45
	s_add_i32 m0, s3, 0xc000
	ds_read_b128 v[176:179], v190
	ds_read_b128 v[180:183], v190 offset:16
	ds_read_b128 v[192:195], v190 offset:2048
	ds_read_b128 v[196:199], v190 offset:2064
	ds_read_b128 v[200:203], v190 offset:4096
	ds_read_b128 v[204:207], v190 offset:4112
	ds_read_b128 v[208:211], v190 offset:6144
	ds_read_b128 v[212:215], v190 offset:6160
	global_load_lds_dwordx4 v164, s[20:21]
	s_add_i32 m0, s3, 0xe000
	v_mov_b32_e32 v169, v165
	global_load_lds_dwordx4 v168, s[20:21]
	s_waitcnt vmcnt(8)
	s_waitcnt lgkmcnt(0)
	s_barrier
	s_setprio 1
	s_waitcnt lgkmcnt(0)
	v_mfma_f32_16x16x128_f8f6f4 v[156:159], v[24:31], v[176:183], v[156:159]
	v_mfma_f32_16x16x128_f8f6f4 v[152:155], v[16:23], v[176:183], v[152:155]
	v_mfma_f32_16x16x128_f8f6f4 v[148:151], v[24:31], v[192:199], v[148:151]
	v_mfma_f32_16x16x128_f8f6f4 v[140:143], v[16:23], v[192:199], v[140:143]
	v_mfma_f32_16x16x128_f8f6f4 v[132:135], v[24:31], v[200:207], v[132:135]
	v_mfma_f32_16x16x128_f8f6f4 v[124:127], v[16:23], v[200:207], v[124:127]
	v_mfma_f32_16x16x128_f8f6f4 v[116:119], v[24:31], v[208:215], v[116:119]
	v_mfma_f32_16x16x128_f8f6f4 v[108:111], v[16:23], v[208:215], v[108:111]
	s_setprio 0
	s_setprio 1
	v_mfma_f32_16x16x128_f8f6f4 v[144:147], v[8:15], v[176:183], v[144:147]
	v_mfma_f32_16x16x128_f8f6f4 v[136:139], v[0:7], v[176:183], v[136:139]
	v_mfma_f32_16x16x128_f8f6f4 v[128:131], v[8:15], v[192:199], v[128:131]
	v_mfma_f32_16x16x128_f8f6f4 v[120:123], v[0:7], v[192:199], v[120:123]
	v_mfma_f32_16x16x128_f8f6f4 v[112:115], v[8:15], v[200:207], v[112:115]
	v_mfma_f32_16x16x128_f8f6f4 v[104:107], v[0:7], v[200:207], v[104:107]
	v_mfma_f32_16x16x128_f8f6f4 v[100:103], v[8:15], v[208:215], v[100:103]
	v_mfma_f32_16x16x128_f8f6f4 v[96:99], v[0:7], v[208:215], v[96:99]
	s_setprio 0
	s_barrier
	s_mov_b32 m0, s13
	ds_read_b128 v[192:195], v190 offset:16384
	ds_read_b128 v[196:199], v190 offset:16400
	ds_read_b128 v[200:203], v190 offset:18432
	ds_read_b128 v[204:207], v190 offset:18448
	ds_read_b128 v[208:211], v190 offset:20480
	ds_read_b128 v[212:215], v190 offset:20496
	ds_read_b128 v[216:219], v190 offset:22528
	ds_read_b128 v[220:223], v190 offset:22544
	global_load_lds_dwordx4 v166, s[24:25]
	s_mov_b32 m0, s22
	s_add_u32 s50, s24, 0x58000
	global_load_lds_dwordx4 v170, s[24:25]
	s_addc_u32 s51, s25, 0
	s_mov_b32 m0, s23
	v_mov_b32_e32 v167, v165
	global_load_lds_dwordx4 v166, s[50:51]
	s_mov_b32 m0, s28
	v_mov_b32_e32 v171, v165
	global_load_lds_dwordx4 v170, s[50:51]
	s_waitcnt vmcnt(6)
	s_waitcnt lgkmcnt(0)
	s_barrier
	s_setprio 1
	s_waitcnt lgkmcnt(0)
	v_mfma_f32_16x16x128_f8f6f4 v[92:95], v[24:31], v[192:199], v[92:95]
	v_mfma_f32_16x16x128_f8f6f4 v[88:91], v[16:23], v[192:199], v[88:91]
	s_mov_b32 m0, s3
	v_lshl_add_u64 v[182:183], s[24:25], 0, v[166:167]
	v_mfma_f32_16x16x128_f8f6f4 v[84:87], v[24:31], v[200:207], v[84:87]
	global_load_lds_dwordx4 v164, s[26:27]
	v_mfma_f32_16x16x128_f8f6f4 v[76:79], v[16:23], v[200:207], v[76:79]
	v_mfma_f32_16x16x128_f8f6f4 v[68:71], v[24:31], v[208:215], v[68:71]
	v_mfma_f32_16x16x128_f8f6f4 v[60:63], v[16:23], v[208:215], v[60:63]
	v_mfma_f32_16x16x128_f8f6f4 v[52:55], v[24:31], v[216:223], v[52:55]
	v_mfma_f32_16x16x128_f8f6f4 v[44:47], v[16:23], v[216:223], v[44:47]
	s_mov_b32 m0, s29
	v_lshl_add_u64 v[180:181], s[24:25], 0, v[170:171]
	s_setprio 0
	s_setprio 1
	v_mfma_f32_16x16x128_f8f6f4 v[80:83], v[8:15], v[192:199], v[80:83]
	global_load_lds_dwordx4 v168, s[26:27]
	v_lshl_add_u64 v[178:179], s[26:27], 0, v[164:165]
	v_lshl_add_u64 v[176:177], s[26:27], 0, v[168:169]
	v_mfma_f32_16x16x128_f8f6f4 v[72:75], v[0:7], v[192:199], v[72:75]
	v_mfma_f32_16x16x128_f8f6f4 v[64:67], v[8:15], v[200:207], v[64:67]
	v_mfma_f32_16x16x128_f8f6f4 v[56:59], v[0:7], v[200:207], v[56:59]
	v_mfma_f32_16x16x128_f8f6f4 v[48:51], v[8:15], v[208:215], v[48:51]
	v_mfma_f32_16x16x128_f8f6f4 v[40:43], v[0:7], v[208:215], v[40:43]
	v_mfma_f32_16x16x128_f8f6f4 v[36:39], v[8:15], v[216:223], v[36:39]
	v_mfma_f32_16x16x128_f8f6f4 v[32:35], v[0:7], v[216:223], v[32:35]
	s_setprio 0
	s_barrier
	ds_read_b128 v[0:3], v189 offset:32768
	ds_read_b128 v[4:7], v189 offset:32784
	ds_read_b128 v[8:11], v189 offset:34816
	ds_read_b128 v[12:15], v189 offset:34832
	ds_read_b128 v[16:19], v189 offset:49152
	ds_read_b128 v[20:23], v189 offset:49168
	ds_read_b128 v[24:27], v189 offset:51200
	ds_read_b128 v[28:31], v189 offset:51216
	s_add_u32 s26, s26, 0x58000
	s_addc_u32 s27, s27, 0
	s_mov_b32 m0, s30
	ds_read_b128 v[192:195], v190 offset:32768
	ds_read_b128 v[196:199], v190 offset:32784
	ds_read_b128 v[200:203], v190 offset:34816
	ds_read_b128 v[204:207], v190 offset:34832
	ds_read_b128 v[208:211], v190 offset:36864
	ds_read_b128 v[212:215], v190 offset:36880
	ds_read_b128 v[216:219], v190 offset:38912
	ds_read_b128 v[220:223], v190 offset:38928
	global_load_lds_dwordx4 v164, s[26:27]
	s_mov_b32 m0, s31
	s_nop 0
	global_load_lds_dwordx4 v168, s[26:27]
	s_waitcnt vmcnt(8)
	s_waitcnt lgkmcnt(0)
	s_barrier
	s_setprio 1
	s_waitcnt lgkmcnt(0)
	v_mfma_f32_16x16x128_f8f6f4 v[156:159], v[0:7], v[192:199], v[156:159]
	v_mfma_f32_16x16x128_f8f6f4 v[152:155], v[8:15], v[192:199], v[152:155]
	v_mfma_f32_16x16x128_f8f6f4 v[148:151], v[0:7], v[200:207], v[148:151]
	v_mfma_f32_16x16x128_f8f6f4 v[140:143], v[8:15], v[200:207], v[140:143]
	v_mfma_f32_16x16x128_f8f6f4 v[132:135], v[0:7], v[208:215], v[132:135]
	v_mfma_f32_16x16x128_f8f6f4 v[124:127], v[8:15], v[208:215], v[124:127]
	v_mfma_f32_16x16x128_f8f6f4 v[116:119], v[0:7], v[216:223], v[116:119]
	v_mfma_f32_16x16x128_f8f6f4 v[108:111], v[8:15], v[216:223], v[108:111]
	s_setprio 0
	s_setprio 1
	v_mfma_f32_16x16x128_f8f6f4 v[144:147], v[16:23], v[192:199], v[144:147]
	v_mfma_f32_16x16x128_f8f6f4 v[136:139], v[24:31], v[192:199], v[136:139]
	v_mfma_f32_16x16x128_f8f6f4 v[128:131], v[16:23], v[200:207], v[128:131]
	v_mfma_f32_16x16x128_f8f6f4 v[120:123], v[24:31], v[200:207], v[120:123]
	v_mfma_f32_16x16x128_f8f6f4 v[112:115], v[16:23], v[208:215], v[112:115]
	v_mfma_f32_16x16x128_f8f6f4 v[104:107], v[24:31], v[208:215], v[104:107]
	v_mfma_f32_16x16x128_f8f6f4 v[100:103], v[16:23], v[216:223], v[100:103]
	v_mfma_f32_16x16x128_f8f6f4 v[96:99], v[24:31], v[216:223], v[96:99]
	s_setprio 0
	s_barrier
	s_mov_b32 m0, s35
	v_lshl_add_u64 v[182:183], v[182:183], 0, s[8:9]
	ds_read_b128 v[192:195], v190 offset:49152
	ds_read_b128 v[196:199], v190 offset:49168
	ds_read_b128 v[200:203], v190 offset:51200
	ds_read_b128 v[204:207], v190 offset:51216
	ds_read_b128 v[208:211], v190 offset:53248
	ds_read_b128 v[212:215], v190 offset:53264
	ds_read_b128 v[216:219], v190 offset:55296
	ds_read_b128 v[220:223], v190 offset:55312
	global_load_lds_dwordx4 v[182:183], off
	v_lshl_add_u64 v[180:181], v[180:181], 0, s[8:9]
	s_mov_b32 m0, s36
	s_add_u32 s24, s24, 0x58080
	global_load_lds_dwordx4 v[180:181], off
	s_addc_u32 s25, s25, 0
	s_mov_b32 m0, s39
	v_lshl_add_u64 v[178:179], v[178:179], 0, s[8:9]
	global_load_lds_dwordx4 v166, s[24:25]
	s_mov_b32 m0, s40
	v_lshl_add_u64 v[176:177], v[176:177], 0, s[8:9]
	global_load_lds_dwordx4 v170, s[24:25]
	s_waitcnt vmcnt(6)
	s_waitcnt lgkmcnt(0)
	s_barrier
	s_setprio 1
	s_waitcnt lgkmcnt(0)
	v_mfma_f32_16x16x128_f8f6f4 v[92:95], v[0:7], v[192:199], v[92:95]
	v_mfma_f32_16x16x128_f8f6f4 v[88:91], v[8:15], v[192:199], v[88:91]
	s_mov_b32 m0, s37
	v_mfma_f32_16x16x128_f8f6f4 v[84:87], v[0:7], v[200:207], v[84:87]
	global_load_lds_dwordx4 v[178:179], off
	v_mfma_f32_16x16x128_f8f6f4 v[76:79], v[8:15], v[200:207], v[76:79]
	v_mfma_f32_16x16x128_f8f6f4 v[68:71], v[0:7], v[208:215], v[68:71]
	v_mfma_f32_16x16x128_f8f6f4 v[60:63], v[8:15], v[208:215], v[60:63]
	v_mfma_f32_16x16x128_f8f6f4 v[52:55], v[0:7], v[216:223], v[52:55]
	v_mfma_f32_16x16x128_f8f6f4 v[44:47], v[8:15], v[216:223], v[44:47]
	s_mov_b32 m0, s38
	s_setprio 0
	s_setprio 1
	v_mfma_f32_16x16x128_f8f6f4 v[80:83], v[16:23], v[192:199], v[80:83]
	global_load_lds_dwordx4 v[176:177], off
	v_mfma_f32_16x16x128_f8f6f4 v[72:75], v[24:31], v[192:199], v[72:75]
	v_mfma_f32_16x16x128_f8f6f4 v[64:67], v[16:23], v[200:207], v[64:67]
	v_mfma_f32_16x16x128_f8f6f4 v[56:59], v[24:31], v[200:207], v[56:59]
	v_mfma_f32_16x16x128_f8f6f4 v[48:51], v[16:23], v[208:215], v[48:51]
	v_mfma_f32_16x16x128_f8f6f4 v[40:43], v[24:31], v[208:215], v[40:43]
	v_mfma_f32_16x16x128_f8f6f4 v[36:39], v[16:23], v[216:223], v[36:39]
	v_mfma_f32_16x16x128_f8f6f4 v[32:35], v[24:31], v[216:223], v[32:35]
	s_setprio 0
	s_barrier
	s_add_i32 s48, s48, 2
	s_add_u32 s20, s20, 0x100
	s_addc_u32 s21, s21, 0
	s_add_u32 s45, s45, 0x100
	s_addc_u32 s47, s47, 0
	s_cmp_gt_u32 s48, 19
	s_cbranch_scc0 .LBB0_662
	s_nop 15
	s_nop 15
	s_and_b64 vcc, exec, s[10:11]
	s_cbranch_vccz .LBB0_665
	s_barrier

.LBB0_792:
	ds_read_b128 v[144:147], v142
	ds_read_b128 v[148:151], v142 offset:1024
	ds_read_b128 v[152:155], v142 offset:2048
	ds_read_b128 v[156:159], v142 offset:3072
	ds_read_b128 v[164:167], v142 offset:16384
	ds_read_b128 v[168:171], v142 offset:17408
	ds_read_b128 v[172:175], v142 offset:18432
	ds_read_b128 v[176:179], v142 offset:19456
	s_add_u32 s26, s24, 0xfffc0080
	s_addc_u32 s27, s25, -1
	s_cmp_eq_u32 s49, 12
	s_cselect_b32 s29, s13, s27
	s_cselect_b32 s28, s44, s26
	s_cselect_b32 s27, s11, s48
	s_cselect_b32 s26, s45, s47
	s_add_i32 m0, s3, 0xc000
	ds_read_b128 v[180:183], v143
	ds_read_b128 v[188:191], v143 offset:1024
	ds_read_b128 v[192:195], v143 offset:2048
	ds_read_b128 v[196:199], v143 offset:3072
	ds_read_b128 v[200:203], v143 offset:4096
	ds_read_b128 v[204:207], v143 offset:5120
	ds_read_b128 v[208:211], v143 offset:6144
	ds_read_b128 v[212:215], v143 offset:7168
	global_load_lds_dwordx4 v128, s[24:25]
	s_add_i32 m0, s3, 0xe000
	v_mov_b32_e32 v131, v129
	global_load_lds_dwordx4 v130, s[24:25]
	s_waitcnt vmcnt(8)
	s_waitcnt lgkmcnt(0)
	s_barrier
	s_setprio 1
	s_waitcnt lgkmcnt(0)
	v_mfma_f32_16x16x32_bf16 v[124:127], v[144:147], v[180:183], v[124:127]
	v_mfma_f32_16x16x32_bf16 v[120:123], v[152:155], v[180:183], v[120:123]
	v_mfma_f32_16x16x32_bf16 v[116:119], v[144:147], v[192:195], v[116:119]
	v_mfma_f32_16x16x32_bf16 v[112:115], v[152:155], v[192:195], v[112:115]
	v_mfma_f32_16x16x32_bf16 v[100:103], v[144:147], v[200:203], v[100:103]
	v_mfma_f32_16x16x32_bf16 v[96:99], v[152:155], v[200:203], v[96:99]
	v_mfma_f32_16x16x32_bf16 v[84:87], v[144:147], v[208:211], v[84:87]
	v_mfma_f32_16x16x32_bf16 v[80:83], v[152:155], v[208:211], v[80:83]
	v_mfma_f32_16x16x32_bf16 v[124:127], v[148:151], v[188:191], v[124:127]
	v_mfma_f32_16x16x32_bf16 v[120:123], v[156:159], v[188:191], v[120:123]
	v_mfma_f32_16x16x32_bf16 v[116:119], v[148:151], v[196:199], v[116:119]
	v_mfma_f32_16x16x32_bf16 v[112:115], v[156:159], v[196:199], v[112:115]
	v_mfma_f32_16x16x32_bf16 v[100:103], v[148:151], v[204:207], v[100:103]
	v_mfma_f32_16x16x32_bf16 v[96:99], v[156:159], v[204:207], v[96:99]
	v_mfma_f32_16x16x32_bf16 v[84:87], v[148:151], v[212:215], v[84:87]
	v_mfma_f32_16x16x32_bf16 v[80:83], v[156:159], v[212:215], v[80:83]
	s_setprio 0
	s_setprio 1
	v_mfma_f32_16x16x32_bf16 v[108:111], v[164:167], v[180:183], v[108:111]
	v_mfma_f32_16x16x32_bf16 v[104:107], v[172:175], v[180:183], v[104:107]
	v_mfma_f32_16x16x32_bf16 v[92:95], v[164:167], v[192:195], v[92:95]
	v_mfma_f32_16x16x32_bf16 v[88:91], v[172:175], v[192:195], v[88:91]
	v_mfma_f32_16x16x32_bf16 v[76:79], v[164:167], v[200:203], v[76:79]
	v_mfma_f32_16x16x32_bf16 v[72:75], v[172:175], v[200:203], v[72:75]
	v_mfma_f32_16x16x32_bf16 v[68:71], v[164:167], v[208:211], v[68:71]
	v_mfma_f32_16x16x32_bf16 v[64:67], v[172:175], v[208:211], v[64:67]
	v_mfma_f32_16x16x32_bf16 v[108:111], v[168:171], v[188:191], v[108:111]
	v_mfma_f32_16x16x32_bf16 v[104:107], v[176:179], v[188:191], v[104:107]
	v_mfma_f32_16x16x32_bf16 v[92:95], v[168:171], v[196:199], v[92:95]
	v_mfma_f32_16x16x32_bf16 v[88:91], v[176:179], v[196:199], v[88:91]
	v_mfma_f32_16x16x32_bf16 v[76:79], v[168:171], v[204:207], v[76:79]
	v_mfma_f32_16x16x32_bf16 v[72:75], v[176:179], v[204:207], v[72:75]
	v_mfma_f32_16x16x32_bf16 v[68:71], v[168:171], v[212:215], v[68:71]
	v_mfma_f32_16x16x32_bf16 v[64:67], v[176:179], v[212:215], v[64:67]
	s_setprio 0
	s_barrier
	s_mov_b32 m0, s15
	ds_read_b128 v[180:183], v143 offset:16384
	ds_read_b128 v[188:191], v143 offset:17408
	ds_read_b128 v[192:195], v143 offset:18432
	ds_read_b128 v[196:199], v143 offset:19456
	ds_read_b128 v[200:203], v143 offset:20480
	ds_read_b128 v[204:207], v143 offset:21504
	ds_read_b128 v[208:211], v143 offset:22528
	ds_read_b128 v[212:215], v143 offset:23552
	global_load_lds_dwordx4 v138, s[26:27]
	s_mov_b32 m0, s22
	s_add_u32 s50, s26, 0x40000
	global_load_lds_dwordx4 v132, s[26:27]
	s_addc_u32 s51, s27, 0
	s_mov_b32 m0, s23
	v_mov_b32_e32 v139, v129
	global_load_lds_dwordx4 v138, s[50:51]
	s_mov_b32 m0, s30
	v_mov_b32_e32 v133, v129
	global_load_lds_dwordx4 v132, s[50:51]
	s_waitcnt vmcnt(6)
	s_waitcnt lgkmcnt(0)
	s_barrier
	s_setprio 1
	s_waitcnt lgkmcnt(0)
	v_mfma_f32_16x16x32_bf16 v[60:63], v[144:147], v[180:183], v[60:63]
	v_mfma_f32_16x16x32_bf16 v[56:59], v[152:155], v[180:183], v[56:59]
	s_mov_b32 m0, s3
	v_lshl_add_u64 v[216:217], s[26:27], 0, v[138:139]
	v_mfma_f32_16x16x32_bf16 v[52:55], v[144:147], v[192:195], v[52:55]
	global_load_lds_dwordx4 v128, s[28:29]
	v_mfma_f32_16x16x32_bf16 v[48:51], v[152:155], v[192:195], v[48:51]
	v_mfma_f32_16x16x32_bf16 v[36:39], v[144:147], v[200:203], v[36:39]
	v_mfma_f32_16x16x32_bf16 v[32:35], v[152:155], v[200:203], v[32:35]
	v_mfma_f32_16x16x32_bf16 v[20:23], v[144:147], v[208:211], v[20:23]
	v_mfma_f32_16x16x32_bf16 v[16:19], v[152:155], v[208:211], v[16:19]
	v_mfma_f32_16x16x32_bf16 v[60:63], v[148:151], v[188:191], v[60:63]
	v_mfma_f32_16x16x32_bf16 v[56:59], v[156:159], v[188:191], v[56:59]
	v_mfma_f32_16x16x32_bf16 v[52:55], v[148:151], v[196:199], v[52:55]
	v_mfma_f32_16x16x32_bf16 v[48:51], v[156:159], v[196:199], v[48:51]
	v_mfma_f32_16x16x32_bf16 v[36:39], v[148:151], v[204:207], v[36:39]
	v_mfma_f32_16x16x32_bf16 v[32:35], v[156:159], v[204:207], v[32:35]
	v_mfma_f32_16x16x32_bf16 v[20:23], v[148:151], v[212:215], v[20:23]
	v_mfma_f32_16x16x32_bf16 v[16:19], v[156:159], v[212:215], v[16:19]
	s_mov_b32 m0, s31
	v_lshl_add_u64 v[218:219], s[26:27], 0, v[132:133]
	s_setprio 0
	s_setprio 1
	v_mfma_f32_16x16x32_bf16 v[44:47], v[164:167], v[180:183], v[44:47]
	global_load_lds_dwordx4 v130, s[28:29]
	v_lshl_add_u64 v[220:221], s[28:29], 0, v[128:129]
	v_lshl_add_u64 v[222:223], s[28:29], 0, v[130:131]
	v_mfma_f32_16x16x32_bf16 v[40:43], v[172:175], v[180:183], v[40:43]
	v_mfma_f32_16x16x32_bf16 v[28:31], v[164:167], v[192:195], v[28:31]
	v_mfma_f32_16x16x32_bf16 v[24:27], v[172:175], v[192:195], v[24:27]
	v_mfma_f32_16x16x32_bf16 v[12:15], v[164:167], v[200:203], v[12:15]
	v_mfma_f32_16x16x32_bf16 v[8:11], v[172:175], v[200:203], v[8:11]
	v_mfma_f32_16x16x32_bf16 v[4:7], v[164:167], v[208:211], v[4:7]
	v_mfma_f32_16x16x32_bf16 v[0:3], v[172:175], v[208:211], v[0:3]
	v_mfma_f32_16x16x32_bf16 v[44:47], v[168:171], v[188:191], v[44:47]
	v_mfma_f32_16x16x32_bf16 v[40:43], v[176:179], v[188:191], v[40:43]
	v_mfma_f32_16x16x32_bf16 v[28:31], v[168:171], v[196:199], v[28:31]
	v_mfma_f32_16x16x32_bf16 v[24:27], v[176:179], v[196:199], v[24:27]
	v_mfma_f32_16x16x32_bf16 v[12:15], v[168:171], v[204:207], v[12:15]
	v_mfma_f32_16x16x32_bf16 v[8:11], v[176:179], v[204:207], v[8:11]
	v_mfma_f32_16x16x32_bf16 v[4:7], v[168:171], v[212:215], v[4:7]
	v_mfma_f32_16x16x32_bf16 v[0:3], v[176:179], v[212:215], v[0:3]
	s_setprio 0
	s_barrier
	ds_read_b128 v[144:147], v142 offset:32768
	ds_read_b128 v[148:151], v142 offset:33792
	ds_read_b128 v[152:155], v142 offset:34816
	ds_read_b128 v[156:159], v142 offset:35840
	ds_read_b128 v[164:167], v142 offset:49152
	ds_read_b128 v[168:171], v142 offset:50176
	ds_read_b128 v[172:175], v142 offset:51200
	ds_read_b128 v[176:179], v142 offset:52224
	s_add_u32 s28, s28, 0x40000
	s_addc_u32 s29, s29, 0
	s_mov_b32 m0, s34
	ds_read_b128 v[180:183], v143 offset:32768
	ds_read_b128 v[188:191], v143 offset:33792
	ds_read_b128 v[192:195], v143 offset:34816
	ds_read_b128 v[196:199], v143 offset:35840
	ds_read_b128 v[200:203], v143 offset:36864
	ds_read_b128 v[204:207], v143 offset:37888
	ds_read_b128 v[208:211], v143 offset:38912
	ds_read_b128 v[212:215], v143 offset:39936
	global_load_lds_dwordx4 v128, s[28:29]
	s_mov_b32 m0, s35
	s_nop 0
	global_load_lds_dwordx4 v130, s[28:29]
	s_waitcnt vmcnt(8)
	s_waitcnt lgkmcnt(0)
	s_barrier
	s_setprio 1
	s_waitcnt lgkmcnt(0)
	v_mfma_f32_16x16x32_bf16 v[124:127], v[144:147], v[180:183], v[124:127]
	v_mfma_f32_16x16x32_bf16 v[120:123], v[152:155], v[180:183], v[120:123]
	v_mfma_f32_16x16x32_bf16 v[116:119], v[144:147], v[192:195], v[116:119]
	v_mfma_f32_16x16x32_bf16 v[112:115], v[152:155], v[192:195], v[112:115]
	v_mfma_f32_16x16x32_bf16 v[100:103], v[144:147], v[200:203], v[100:103]
	v_mfma_f32_16x16x32_bf16 v[96:99], v[152:155], v[200:203], v[96:99]
	v_mfma_f32_16x16x32_bf16 v[84:87], v[144:147], v[208:211], v[84:87]
	v_mfma_f32_16x16x32_bf16 v[80:83], v[152:155], v[208:211], v[80:83]
	v_mfma_f32_16x16x32_bf16 v[124:127], v[148:151], v[188:191], v[124:127]
	v_mfma_f32_16x16x32_bf16 v[120:123], v[156:159], v[188:191], v[120:123]
	v_mfma_f32_16x16x32_bf16 v[116:119], v[148:151], v[196:199], v[116:119]
	v_mfma_f32_16x16x32_bf16 v[112:115], v[156:159], v[196:199], v[112:115]
	v_mfma_f32_16x16x32_bf16 v[100:103], v[148:151], v[204:207], v[100:103]
	v_mfma_f32_16x16x32_bf16 v[96:99], v[156:159], v[204:207], v[96:99]
	v_mfma_f32_16x16x32_bf16 v[84:87], v[148:151], v[212:215], v[84:87]
	v_mfma_f32_16x16x32_bf16 v[80:83], v[156:159], v[212:215], v[80:83]
	s_setprio 0
	s_setprio 1
	v_mfma_f32_16x16x32_bf16 v[108:111], v[164:167], v[180:183], v[108:111]
	v_mfma_f32_16x16x32_bf16 v[104:107], v[172:175], v[180:183], v[104:107]
	v_mfma_f32_16x16x32_bf16 v[92:95], v[164:167], v[192:195], v[92:95]
	v_mfma_f32_16x16x32_bf16 v[88:91], v[172:175], v[192:195], v[88:91]
	v_mfma_f32_16x16x32_bf16 v[76:79], v[164:167], v[200:203], v[76:79]
	v_mfma_f32_16x16x32_bf16 v[72:75], v[172:175], v[200:203], v[72:75]
	v_mfma_f32_16x16x32_bf16 v[68:71], v[164:167], v[208:211], v[68:71]
	v_mfma_f32_16x16x32_bf16 v[64:67], v[172:175], v[208:211], v[64:67]
	v_mfma_f32_16x16x32_bf16 v[108:111], v[168:171], v[188:191], v[108:111]
	v_mfma_f32_16x16x32_bf16 v[104:107], v[176:179], v[188:191], v[104:107]
	v_mfma_f32_16x16x32_bf16 v[92:95], v[168:171], v[196:199], v[92:95]
	v_mfma_f32_16x16x32_bf16 v[88:91], v[176:179], v[196:199], v[88:91]
	v_mfma_f32_16x16x32_bf16 v[76:79], v[168:171], v[204:207], v[76:79]
	v_mfma_f32_16x16x32_bf16 v[72:75], v[176:179], v[204:207], v[72:75]
	v_mfma_f32_16x16x32_bf16 v[68:71], v[168:171], v[212:215], v[68:71]
	v_mfma_f32_16x16x32_bf16 v[64:67], v[176:179], v[212:215], v[64:67]
	s_setprio 0
	s_barrier
	s_mov_b32 m0, s37
	v_lshl_add_u64 v[216:217], v[216:217], 0, s[6:7]
	ds_read_b128 v[180:183], v143 offset:49152
	ds_read_b128 v[188:191], v143 offset:50176
	ds_read_b128 v[192:195], v143 offset:51200
	ds_read_b128 v[196:199], v143 offset:52224
	ds_read_b128 v[200:203], v143 offset:53248
	ds_read_b128 v[204:207], v143 offset:54272
	ds_read_b128 v[208:211], v143 offset:55296
	ds_read_b128 v[212:215], v143 offset:56320
	global_load_lds_dwordx4 v[216:217], off
	v_lshl_add_u64 v[216:217], v[218:219], 0, s[6:7]
	s_mov_b32 m0, s38
	s_add_u32 s26, s26, 0x40080
	global_load_lds_dwordx4 v[216:217], off
	s_addc_u32 s27, s27, 0
	s_mov_b32 m0, s41
	v_lshl_add_u64 v[216:217], v[220:221], 0, s[6:7]
	global_load_lds_dwordx4 v138, s[26:27]
	s_mov_b32 m0, s42
	s_nop 0
	global_load_lds_dwordx4 v132, s[26:27]
	s_waitcnt vmcnt(6)
	s_waitcnt lgkmcnt(0)
	s_barrier
	s_setprio 1
	s_waitcnt lgkmcnt(0)
	v_mfma_f32_16x16x32_bf16 v[60:63], v[144:147], v[180:183], v[60:63]
	v_mfma_f32_16x16x32_bf16 v[56:59], v[152:155], v[180:183], v[56:59]
	s_mov_b32 m0, s39
	v_mfma_f32_16x16x32_bf16 v[52:55], v[144:147], v[192:195], v[52:55]
	global_load_lds_dwordx4 v[216:217], off
	v_mfma_f32_16x16x32_bf16 v[48:51], v[152:155], v[192:195], v[48:51]
	v_mfma_f32_16x16x32_bf16 v[36:39], v[144:147], v[200:203], v[36:39]
	v_mfma_f32_16x16x32_bf16 v[32:35], v[152:155], v[200:203], v[32:35]
	v_mfma_f32_16x16x32_bf16 v[20:23], v[144:147], v[208:211], v[20:23]
	v_mfma_f32_16x16x32_bf16 v[16:19], v[152:155], v[208:211], v[16:19]
	v_mfma_f32_16x16x32_bf16 v[60:63], v[148:151], v[188:191], v[60:63]
	v_mfma_f32_16x16x32_bf16 v[56:59], v[156:159], v[188:191], v[56:59]
	v_mfma_f32_16x16x32_bf16 v[52:55], v[148:151], v[196:199], v[52:55]
	v_mfma_f32_16x16x32_bf16 v[48:51], v[156:159], v[196:199], v[48:51]
	v_mfma_f32_16x16x32_bf16 v[36:39], v[148:151], v[204:207], v[36:39]
	v_mfma_f32_16x16x32_bf16 v[32:35], v[156:159], v[204:207], v[32:35]
	v_mfma_f32_16x16x32_bf16 v[20:23], v[148:151], v[212:215], v[20:23]
	v_mfma_f32_16x16x32_bf16 v[16:19], v[156:159], v[212:215], v[16:19]
	v_lshl_add_u64 v[216:217], v[222:223], 0, s[6:7]
	s_mov_b32 m0, s40
	s_setprio 0
	s_setprio 1
	v_mfma_f32_16x16x32_bf16 v[44:47], v[164:167], v[180:183], v[44:47]
	global_load_lds_dwordx4 v[216:217], off
	v_mfma_f32_16x16x32_bf16 v[40:43], v[172:175], v[180:183], v[40:43]
	v_mfma_f32_16x16x32_bf16 v[28:31], v[164:167], v[192:195], v[28:31]
	v_mfma_f32_16x16x32_bf16 v[24:27], v[172:175], v[192:195], v[24:27]
	v_mfma_f32_16x16x32_bf16 v[12:15], v[164:167], v[200:203], v[12:15]
	v_mfma_f32_16x16x32_bf16 v[8:11], v[172:175], v[200:203], v[8:11]
	v_mfma_f32_16x16x32_bf16 v[4:7], v[164:167], v[208:211], v[4:7]
	v_mfma_f32_16x16x32_bf16 v[0:3], v[172:175], v[208:211], v[0:3]
	v_mfma_f32_16x16x32_bf16 v[44:47], v[168:171], v[188:191], v[44:47]
	v_mfma_f32_16x16x32_bf16 v[40:43], v[176:179], v[188:191], v[40:43]
	v_mfma_f32_16x16x32_bf16 v[28:31], v[168:171], v[196:199], v[28:31]
	v_mfma_f32_16x16x32_bf16 v[24:27], v[176:179], v[196:199], v[24:27]
	v_mfma_f32_16x16x32_bf16 v[12:15], v[168:171], v[204:207], v[12:15]
	v_mfma_f32_16x16x32_bf16 v[8:11], v[176:179], v[204:207], v[8:11]
	v_mfma_f32_16x16x32_bf16 v[4:7], v[168:171], v[212:215], v[4:7]
	v_mfma_f32_16x16x32_bf16 v[0:3], v[176:179], v[212:215], v[0:3]
	s_setprio 0
	s_barrier
	s_add_i32 s49, s49, 2
	s_add_u32 s24, s24, 0x100
	s_addc_u32 s25, s25, 0
	s_add_u32 s47, s47, 0x100
	s_addc_u32 s48, s48, 0
	s_cmp_gt_u32 s49, 13
	s_cbranch_scc0 .LBB0_792
	s_and_b64 vcc, exec, s[8:9]
	s_cbranch_vccz .LBB0_795
	s_barrier

.LBB0_993:
	ds_read_b128 v[144:147], v142
	ds_read_b128 v[148:151], v142 offset:1024
	ds_read_b128 v[152:155], v142 offset:2048
	ds_read_b128 v[156:159], v142 offset:3072
	ds_read_b128 v[164:167], v142 offset:16384
	ds_read_b128 v[168:171], v142 offset:17408
	ds_read_b128 v[172:175], v142 offset:18432
	ds_read_b128 v[176:179], v142 offset:19456
	s_add_u32 s28, s26, 0xfffc0080
	s_addc_u32 s29, s27, -1
	s_cmp_eq_u32 s54, 12
	s_cselect_b32 s31, s17, s29
	s_cselect_b32 s30, s50, s28
	s_cselect_b32 s29, s15, s53
	s_cselect_b32 s28, s51, s52
	s_add_i32 m0, s3, 0xc000
	ds_read_b128 v[180:183], v143
	ds_read_b128 v[188:191], v143 offset:1024
	ds_read_b128 v[192:195], v143 offset:2048
	ds_read_b128 v[196:199], v143 offset:3072
	ds_read_b128 v[200:203], v143 offset:4096
	ds_read_b128 v[204:207], v143 offset:5120
	ds_read_b128 v[208:211], v143 offset:6144
	ds_read_b128 v[212:215], v143 offset:7168
	global_load_lds_dwordx4 v128, s[26:27]
	s_add_i32 m0, s3, 0xe000
	v_mov_b32_e32 v131, v129
	global_load_lds_dwordx4 v130, s[26:27]
	s_waitcnt vmcnt(8)
	s_waitcnt lgkmcnt(0)
	s_barrier
	s_setprio 1
	s_waitcnt lgkmcnt(0)
	v_mfma_f32_16x16x32_bf16 v[124:127], v[144:147], v[180:183], v[124:127]
	v_mfma_f32_16x16x32_bf16 v[120:123], v[152:155], v[180:183], v[120:123]
	v_mfma_f32_16x16x32_bf16 v[116:119], v[144:147], v[192:195], v[116:119]
	v_mfma_f32_16x16x32_bf16 v[112:115], v[152:155], v[192:195], v[112:115]
	v_mfma_f32_16x16x32_bf16 v[100:103], v[144:147], v[200:203], v[100:103]
	v_mfma_f32_16x16x32_bf16 v[96:99], v[152:155], v[200:203], v[96:99]
	v_mfma_f32_16x16x32_bf16 v[84:87], v[144:147], v[208:211], v[84:87]
	v_mfma_f32_16x16x32_bf16 v[80:83], v[152:155], v[208:211], v[80:83]
	v_mfma_f32_16x16x32_bf16 v[124:127], v[148:151], v[188:191], v[124:127]
	v_mfma_f32_16x16x32_bf16 v[120:123], v[156:159], v[188:191], v[120:123]
	v_mfma_f32_16x16x32_bf16 v[116:119], v[148:151], v[196:199], v[116:119]
	v_mfma_f32_16x16x32_bf16 v[112:115], v[156:159], v[196:199], v[112:115]
	v_mfma_f32_16x16x32_bf16 v[100:103], v[148:151], v[204:207], v[100:103]
	v_mfma_f32_16x16x32_bf16 v[96:99], v[156:159], v[204:207], v[96:99]
	v_mfma_f32_16x16x32_bf16 v[84:87], v[148:151], v[212:215], v[84:87]
	v_mfma_f32_16x16x32_bf16 v[80:83], v[156:159], v[212:215], v[80:83]
	s_setprio 0
	s_setprio 1
	v_mfma_f32_16x16x32_bf16 v[108:111], v[164:167], v[180:183], v[108:111]
	v_mfma_f32_16x16x32_bf16 v[104:107], v[172:175], v[180:183], v[104:107]
	v_mfma_f32_16x16x32_bf16 v[92:95], v[164:167], v[192:195], v[92:95]
	v_mfma_f32_16x16x32_bf16 v[88:91], v[172:175], v[192:195], v[88:91]
	v_mfma_f32_16x16x32_bf16 v[76:79], v[164:167], v[200:203], v[76:79]
	v_mfma_f32_16x16x32_bf16 v[72:75], v[172:175], v[200:203], v[72:75]
	v_mfma_f32_16x16x32_bf16 v[68:71], v[164:167], v[208:211], v[68:71]
	v_mfma_f32_16x16x32_bf16 v[64:67], v[172:175], v[208:211], v[64:67]
	v_mfma_f32_16x16x32_bf16 v[108:111], v[168:171], v[188:191], v[108:111]
	v_mfma_f32_16x16x32_bf16 v[104:107], v[176:179], v[188:191], v[104:107]
	v_mfma_f32_16x16x32_bf16 v[92:95], v[168:171], v[196:199], v[92:95]
	v_mfma_f32_16x16x32_bf16 v[88:91], v[176:179], v[196:199], v[88:91]
	v_mfma_f32_16x16x32_bf16 v[76:79], v[168:171], v[204:207], v[76:79]
	v_mfma_f32_16x16x32_bf16 v[72:75], v[176:179], v[204:207], v[72:75]
	v_mfma_f32_16x16x32_bf16 v[68:71], v[168:171], v[212:215], v[68:71]
	v_mfma_f32_16x16x32_bf16 v[64:67], v[176:179], v[212:215], v[64:67]
	s_setprio 0
	s_barrier
	s_mov_b32 m0, s19
	ds_read_b128 v[180:183], v143 offset:16384
	ds_read_b128 v[188:191], v143 offset:17408
	ds_read_b128 v[192:195], v143 offset:18432
	ds_read_b128 v[196:199], v143 offset:19456
	ds_read_b128 v[200:203], v143 offset:20480
	ds_read_b128 v[204:207], v143 offset:21504
	ds_read_b128 v[208:211], v143 offset:22528
	ds_read_b128 v[212:215], v143 offset:23552
	global_load_lds_dwordx4 v138, s[28:29]
	s_mov_b32 m0, s22
	s_add_u32 s62, s28, 0x40000
	global_load_lds_dwordx4 v132, s[28:29]
	s_addc_u32 s63, s29, 0
	s_mov_b32 m0, s23
	v_mov_b32_e32 v139, v129
	global_load_lds_dwordx4 v138, s[62:63]
	s_mov_b32 m0, s34
	v_mov_b32_e32 v133, v129
	global_load_lds_dwordx4 v132, s[62:63]
	s_waitcnt vmcnt(6)
	s_waitcnt lgkmcnt(0)
	s_barrier
	s_setprio 1
	s_waitcnt lgkmcnt(0)
	v_mfma_f32_16x16x32_bf16 v[60:63], v[144:147], v[180:183], v[60:63]
	v_mfma_f32_16x16x32_bf16 v[56:59], v[152:155], v[180:183], v[56:59]
	s_mov_b32 m0, s3
	v_lshl_add_u64 v[216:217], s[28:29], 0, v[138:139]
	v_mfma_f32_16x16x32_bf16 v[52:55], v[144:147], v[192:195], v[52:55]
	global_load_lds_dwordx4 v128, s[30:31]
	v_mfma_f32_16x16x32_bf16 v[48:51], v[152:155], v[192:195], v[48:51]
	v_mfma_f32_16x16x32_bf16 v[36:39], v[144:147], v[200:203], v[36:39]
	v_mfma_f32_16x16x32_bf16 v[32:35], v[152:155], v[200:203], v[32:35]
	v_mfma_f32_16x16x32_bf16 v[20:23], v[144:147], v[208:211], v[20:23]
	v_mfma_f32_16x16x32_bf16 v[16:19], v[152:155], v[208:211], v[16:19]
	v_mfma_f32_16x16x32_bf16 v[60:63], v[148:151], v[188:191], v[60:63]
	v_mfma_f32_16x16x32_bf16 v[56:59], v[156:159], v[188:191], v[56:59]
	v_mfma_f32_16x16x32_bf16 v[52:55], v[148:151], v[196:199], v[52:55]
	v_mfma_f32_16x16x32_bf16 v[48:51], v[156:159], v[196:199], v[48:51]
	v_mfma_f32_16x16x32_bf16 v[36:39], v[148:151], v[204:207], v[36:39]
	v_mfma_f32_16x16x32_bf16 v[32:35], v[156:159], v[204:207], v[32:35]
	v_mfma_f32_16x16x32_bf16 v[20:23], v[148:151], v[212:215], v[20:23]
	v_mfma_f32_16x16x32_bf16 v[16:19], v[156:159], v[212:215], v[16:19]
	s_mov_b32 m0, s35
	v_lshl_add_u64 v[218:219], s[28:29], 0, v[132:133]
	s_setprio 0
	s_setprio 1
	v_mfma_f32_16x16x32_bf16 v[44:47], v[164:167], v[180:183], v[44:47]
	global_load_lds_dwordx4 v130, s[30:31]
	v_lshl_add_u64 v[220:221], s[30:31], 0, v[128:129]
	v_lshl_add_u64 v[222:223], s[30:31], 0, v[130:131]
	v_mfma_f32_16x16x32_bf16 v[40:43], v[172:175], v[180:183], v[40:43]
	v_mfma_f32_16x16x32_bf16 v[28:31], v[164:167], v[192:195], v[28:31]
	v_mfma_f32_16x16x32_bf16 v[24:27], v[172:175], v[192:195], v[24:27]
	v_mfma_f32_16x16x32_bf16 v[12:15], v[164:167], v[200:203], v[12:15]
	v_mfma_f32_16x16x32_bf16 v[8:11], v[172:175], v[200:203], v[8:11]
	v_mfma_f32_16x16x32_bf16 v[4:7], v[164:167], v[208:211], v[4:7]
	v_mfma_f32_16x16x32_bf16 v[0:3], v[172:175], v[208:211], v[0:3]
	v_mfma_f32_16x16x32_bf16 v[44:47], v[168:171], v[188:191], v[44:47]
	v_mfma_f32_16x16x32_bf16 v[40:43], v[176:179], v[188:191], v[40:43]
	v_mfma_f32_16x16x32_bf16 v[28:31], v[168:171], v[196:199], v[28:31]
	v_mfma_f32_16x16x32_bf16 v[24:27], v[176:179], v[196:199], v[24:27]
	v_mfma_f32_16x16x32_bf16 v[12:15], v[168:171], v[204:207], v[12:15]
	v_mfma_f32_16x16x32_bf16 v[8:11], v[176:179], v[204:207], v[8:11]
	v_mfma_f32_16x16x32_bf16 v[4:7], v[168:171], v[212:215], v[4:7]
	v_mfma_f32_16x16x32_bf16 v[0:3], v[176:179], v[212:215], v[0:3]
	s_setprio 0
	s_barrier
	ds_read_b128 v[144:147], v142 offset:32768
	ds_read_b128 v[148:151], v142 offset:33792
	ds_read_b128 v[152:155], v142 offset:34816
	ds_read_b128 v[156:159], v142 offset:35840
	ds_read_b128 v[164:167], v142 offset:49152
	ds_read_b128 v[168:171], v142 offset:50176
	ds_read_b128 v[172:175], v142 offset:51200
	ds_read_b128 v[176:179], v142 offset:52224
	s_add_u32 s30, s30, 0x40000
	s_addc_u32 s31, s31, 0
	s_mov_b32 m0, s36
	ds_read_b128 v[180:183], v143 offset:32768
	ds_read_b128 v[188:191], v143 offset:33792
	ds_read_b128 v[192:195], v143 offset:34816
	ds_read_b128 v[196:199], v143 offset:35840
	ds_read_b128 v[200:203], v143 offset:36864
	ds_read_b128 v[204:207], v143 offset:37888
	ds_read_b128 v[208:211], v143 offset:38912
	ds_read_b128 v[212:215], v143 offset:39936
	global_load_lds_dwordx4 v128, s[30:31]
	s_mov_b32 m0, s37
	s_nop 0
	global_load_lds_dwordx4 v130, s[30:31]
	s_waitcnt vmcnt(8)
	s_waitcnt lgkmcnt(0)
	s_barrier
	s_setprio 1
	s_waitcnt lgkmcnt(0)
	v_mfma_f32_16x16x32_bf16 v[124:127], v[144:147], v[180:183], v[124:127]
	v_mfma_f32_16x16x32_bf16 v[120:123], v[152:155], v[180:183], v[120:123]
	v_mfma_f32_16x16x32_bf16 v[116:119], v[144:147], v[192:195], v[116:119]
	v_mfma_f32_16x16x32_bf16 v[112:115], v[152:155], v[192:195], v[112:115]
	v_mfma_f32_16x16x32_bf16 v[100:103], v[144:147], v[200:203], v[100:103]
	v_mfma_f32_16x16x32_bf16 v[96:99], v[152:155], v[200:203], v[96:99]
	v_mfma_f32_16x16x32_bf16 v[84:87], v[144:147], v[208:211], v[84:87]
	v_mfma_f32_16x16x32_bf16 v[80:83], v[152:155], v[208:211], v[80:83]
	v_mfma_f32_16x16x32_bf16 v[124:127], v[148:151], v[188:191], v[124:127]
	v_mfma_f32_16x16x32_bf16 v[120:123], v[156:159], v[188:191], v[120:123]
	v_mfma_f32_16x16x32_bf16 v[116:119], v[148:151], v[196:199], v[116:119]
	v_mfma_f32_16x16x32_bf16 v[112:115], v[156:159], v[196:199], v[112:115]
	v_mfma_f32_16x16x32_bf16 v[100:103], v[148:151], v[204:207], v[100:103]
	v_mfma_f32_16x16x32_bf16 v[96:99], v[156:159], v[204:207], v[96:99]
	v_mfma_f32_16x16x32_bf16 v[84:87], v[148:151], v[212:215], v[84:87]
	v_mfma_f32_16x16x32_bf16 v[80:83], v[156:159], v[212:215], v[80:83]
	s_setprio 0
	s_setprio 1
	v_mfma_f32_16x16x32_bf16 v[108:111], v[164:167], v[180:183], v[108:111]
	v_mfma_f32_16x16x32_bf16 v[104:107], v[172:175], v[180:183], v[104:107]
	v_mfma_f32_16x16x32_bf16 v[92:95], v[164:167], v[192:195], v[92:95]
	v_mfma_f32_16x16x32_bf16 v[88:91], v[172:175], v[192:195], v[88:91]
	v_mfma_f32_16x16x32_bf16 v[76:79], v[164:167], v[200:203], v[76:79]
	v_mfma_f32_16x16x32_bf16 v[72:75], v[172:175], v[200:203], v[72:75]
	v_mfma_f32_16x16x32_bf16 v[68:71], v[164:167], v[208:211], v[68:71]
	v_mfma_f32_16x16x32_bf16 v[64:67], v[172:175], v[208:211], v[64:67]
	v_mfma_f32_16x16x32_bf16 v[108:111], v[168:171], v[188:191], v[108:111]
	v_mfma_f32_16x16x32_bf16 v[104:107], v[176:179], v[188:191], v[104:107]
	v_mfma_f32_16x16x32_bf16 v[92:95], v[168:171], v[196:199], v[92:95]
	v_mfma_f32_16x16x32_bf16 v[88:91], v[176:179], v[196:199], v[88:91]
	v_mfma_f32_16x16x32_bf16 v[76:79], v[168:171], v[204:207], v[76:79]
	v_mfma_f32_16x16x32_bf16 v[72:75], v[176:179], v[204:207], v[72:75]
	v_mfma_f32_16x16x32_bf16 v[68:71], v[168:171], v[212:215], v[68:71]
	v_mfma_f32_16x16x32_bf16 v[64:67], v[176:179], v[212:215], v[64:67]
	s_setprio 0
	s_barrier
	s_mov_b32 m0, s39
	v_lshl_add_u64 v[216:217], v[216:217], 0, s[6:7]
	ds_read_b128 v[180:183], v143 offset:49152
	ds_read_b128 v[188:191], v143 offset:50176
	ds_read_b128 v[192:195], v143 offset:51200
	ds_read_b128 v[196:199], v143 offset:52224
	ds_read_b128 v[200:203], v143 offset:53248
	ds_read_b128 v[204:207], v143 offset:54272
	ds_read_b128 v[208:211], v143 offset:55296
	ds_read_b128 v[212:215], v143 offset:56320
	global_load_lds_dwordx4 v[216:217], off
	v_lshl_add_u64 v[216:217], v[218:219], 0, s[6:7]
	s_mov_b32 m0, s40
	s_add_u32 s28, s28, 0x40080
	global_load_lds_dwordx4 v[216:217], off
	s_addc_u32 s29, s29, 0
	s_mov_b32 m0, s43
	v_lshl_add_u64 v[216:217], v[220:221], 0, s[6:7]
	global_load_lds_dwordx4 v138, s[28:29]
	s_mov_b32 m0, s44
	s_nop 0
	global_load_lds_dwordx4 v132, s[28:29]
	s_waitcnt vmcnt(6)
	s_waitcnt lgkmcnt(0)
	s_barrier
	s_setprio 1
	s_waitcnt lgkmcnt(0)
	v_mfma_f32_16x16x32_bf16 v[60:63], v[144:147], v[180:183], v[60:63]
	v_mfma_f32_16x16x32_bf16 v[56:59], v[152:155], v[180:183], v[56:59]
	s_mov_b32 m0, s41
	v_mfma_f32_16x16x32_bf16 v[52:55], v[144:147], v[192:195], v[52:55]
	global_load_lds_dwordx4 v[216:217], off
	v_mfma_f32_16x16x32_bf16 v[48:51], v[152:155], v[192:195], v[48:51]
	v_mfma_f32_16x16x32_bf16 v[36:39], v[144:147], v[200:203], v[36:39]
	v_mfma_f32_16x16x32_bf16 v[32:35], v[152:155], v[200:203], v[32:35]
	v_mfma_f32_16x16x32_bf16 v[20:23], v[144:147], v[208:211], v[20:23]
	v_mfma_f32_16x16x32_bf16 v[16:19], v[152:155], v[208:211], v[16:19]
	v_mfma_f32_16x16x32_bf16 v[60:63], v[148:151], v[188:191], v[60:63]
	v_mfma_f32_16x16x32_bf16 v[56:59], v[156:159], v[188:191], v[56:59]
	v_mfma_f32_16x16x32_bf16 v[52:55], v[148:151], v[196:199], v[52:55]
	v_mfma_f32_16x16x32_bf16 v[48:51], v[156:159], v[196:199], v[48:51]
	v_mfma_f32_16x16x32_bf16 v[36:39], v[148:151], v[204:207], v[36:39]
	v_mfma_f32_16x16x32_bf16 v[32:35], v[156:159], v[204:207], v[32:35]
	v_mfma_f32_16x16x32_bf16 v[20:23], v[148:151], v[212:215], v[20:23]
	v_mfma_f32_16x16x32_bf16 v[16:19], v[156:159], v[212:215], v[16:19]
	v_lshl_add_u64 v[216:217], v[222:223], 0, s[6:7]
	s_mov_b32 m0, s42
	s_setprio 0
	s_setprio 1
	v_mfma_f32_16x16x32_bf16 v[44:47], v[164:167], v[180:183], v[44:47]
	global_load_lds_dwordx4 v[216:217], off
	v_mfma_f32_16x16x32_bf16 v[40:43], v[172:175], v[180:183], v[40:43]
	v_mfma_f32_16x16x32_bf16 v[28:31], v[164:167], v[192:195], v[28:31]
	v_mfma_f32_16x16x32_bf16 v[24:27], v[172:175], v[192:195], v[24:27]
	v_mfma_f32_16x16x32_bf16 v[12:15], v[164:167], v[200:203], v[12:15]
	v_mfma_f32_16x16x32_bf16 v[8:11], v[172:175], v[200:203], v[8:11]
	v_mfma_f32_16x16x32_bf16 v[4:7], v[164:167], v[208:211], v[4:7]
	v_mfma_f32_16x16x32_bf16 v[0:3], v[172:175], v[208:211], v[0:3]
	v_mfma_f32_16x16x32_bf16 v[44:47], v[168:171], v[188:191], v[44:47]
	v_mfma_f32_16x16x32_bf16 v[40:43], v[176:179], v[188:191], v[40:43]
	v_mfma_f32_16x16x32_bf16 v[28:31], v[168:171], v[196:199], v[28:31]
	v_mfma_f32_16x16x32_bf16 v[24:27], v[176:179], v[196:199], v[24:27]
	v_mfma_f32_16x16x32_bf16 v[12:15], v[168:171], v[204:207], v[12:15]
	v_mfma_f32_16x16x32_bf16 v[8:11], v[176:179], v[204:207], v[8:11]
	v_mfma_f32_16x16x32_bf16 v[4:7], v[168:171], v[212:215], v[4:7]
	v_mfma_f32_16x16x32_bf16 v[0:3], v[176:179], v[212:215], v[0:3]
	s_setprio 0
	s_barrier
	s_add_i32 s54, s54, 2
	s_add_u32 s26, s26, 0x100
	s_addc_u32 s27, s27, 0
	s_add_u32 s52, s52, 0x100
	s_addc_u32 s53, s53, 0
	s_cmp_gt_u32 s54, 13
	s_cbranch_scc0 .LBB0_993
	s_and_b64 vcc, exec, s[8:9]
	s_cbranch_vccz .LBB0_996
	s_barrier

.LBB0_1272:
	ds_read_b128 v[24:27], v182
	ds_read_b128 v[28:31], v182 offset:16
	ds_read_b128 v[16:19], v182 offset:2048
	ds_read_b128 v[20:23], v182 offset:2064
	ds_read_b128 v[8:11], v182 offset:16384
	ds_read_b128 v[12:15], v182 offset:16400
	ds_read_b128 v[0:3], v182 offset:18432
	ds_read_b128 v[4:7], v182 offset:18448
	s_add_u32 s30, s28, 0xfffe0080
	s_addc_u32 s31, s29, -1
	s_cmp_eq_u32 s65, 4
	s_cselect_b32 s35, s15, s31
	s_cselect_b32 s34, s57, s30
	s_cselect_b32 s31, s17, s64
	s_cselect_b32 s30, s62, s63
	s_add_i32 m0, s25, 0xc000
	ds_read_b128 v[172:175], v183
	ds_read_b128 v[176:179], v183 offset:16
	ds_read_b128 v[188:191], v183 offset:2048
	ds_read_b128 v[192:195], v183 offset:2064
	ds_read_b128 v[196:199], v183 offset:4096
	ds_read_b128 v[200:203], v183 offset:4112
	ds_read_b128 v[204:207], v183 offset:6144
	ds_read_b128 v[208:211], v183 offset:6160
	global_load_lds_dwordx4 v164, s[28:29]
	s_add_i32 m0, s25, 0xe000
	v_mov_b32_e32 v167, v165
	global_load_lds_dwordx4 v166, s[28:29]
	s_waitcnt vmcnt(8)
	s_waitcnt lgkmcnt(0)
	s_barrier
	s_setprio 1
	s_waitcnt lgkmcnt(0)
	v_mfma_f32_16x16x128_f8f6f4 v[156:159], v[24:31], v[172:179], v[156:159]
	v_mfma_f32_16x16x128_f8f6f4 v[148:151], v[16:23], v[172:179], v[148:151]
	v_mfma_f32_16x16x128_f8f6f4 v[140:143], v[24:31], v[188:195], v[140:143]
	v_mfma_f32_16x16x128_f8f6f4 v[132:135], v[16:23], v[188:195], v[132:135]
	v_mfma_f32_16x16x128_f8f6f4 v[124:127], v[24:31], v[196:203], v[124:127]
	v_mfma_f32_16x16x128_f8f6f4 v[116:119], v[16:23], v[196:203], v[116:119]
	v_mfma_f32_16x16x128_f8f6f4 v[108:111], v[24:31], v[204:211], v[108:111]
	v_mfma_f32_16x16x128_f8f6f4 v[100:103], v[16:23], v[204:211], v[100:103]
	s_setprio 0
	s_setprio 1
	v_mfma_f32_16x16x128_f8f6f4 v[152:155], v[8:15], v[172:179], v[152:155]
	v_mfma_f32_16x16x128_f8f6f4 v[144:147], v[0:7], v[172:179], v[144:147]
	v_mfma_f32_16x16x128_f8f6f4 v[136:139], v[8:15], v[188:195], v[136:139]
	v_mfma_f32_16x16x128_f8f6f4 v[128:131], v[0:7], v[188:195], v[128:131]
	v_mfma_f32_16x16x128_f8f6f4 v[120:123], v[8:15], v[196:203], v[120:123]
	v_mfma_f32_16x16x128_f8f6f4 v[112:115], v[0:7], v[196:203], v[112:115]
	v_mfma_f32_16x16x128_f8f6f4 v[104:107], v[8:15], v[204:211], v[104:107]
	v_mfma_f32_16x16x128_f8f6f4 v[96:99], v[0:7], v[204:211], v[96:99]
	s_setprio 0
	s_barrier
	s_mov_b32 m0, s27
	ds_read_b128 v[188:191], v183 offset:16384
	ds_read_b128 v[192:195], v183 offset:16400
	ds_read_b128 v[196:199], v183 offset:18432
	ds_read_b128 v[200:203], v183 offset:18448
	ds_read_b128 v[204:207], v183 offset:20480
	ds_read_b128 v[208:211], v183 offset:20496
	ds_read_b128 v[212:215], v183 offset:22528
	ds_read_b128 v[216:219], v183 offset:22544
	global_load_lds_dwordx4 v162, s[30:31]
	s_mov_b32 m0, s36
	s_add_u32 s66, s30, 0x20000
	global_load_lds_dwordx4 v168, s[30:31]
	s_addc_u32 s67, s31, 0
	s_mov_b32 m0, s37
	v_mov_b32_e32 v163, v165
	global_load_lds_dwordx4 v162, s[66:67]
	s_mov_b32 m0, s38
	v_mov_b32_e32 v169, v165
	global_load_lds_dwordx4 v168, s[66:67]
	s_waitcnt vmcnt(6)
	s_waitcnt lgkmcnt(0)
	s_barrier
	s_setprio 1
	s_waitcnt lgkmcnt(0)
	v_mfma_f32_16x16x128_f8f6f4 v[92:95], v[24:31], v[188:195], v[92:95]
	v_mfma_f32_16x16x128_f8f6f4 v[84:87], v[16:23], v[188:195], v[84:87]
	s_mov_b32 m0, s25
	v_lshl_add_u64 v[178:179], s[30:31], 0, v[162:163]
	v_mfma_f32_16x16x128_f8f6f4 v[76:79], v[24:31], v[196:203], v[76:79]
	global_load_lds_dwordx4 v164, s[34:35]
	v_mfma_f32_16x16x128_f8f6f4 v[68:71], v[16:23], v[196:203], v[68:71]
	v_mfma_f32_16x16x128_f8f6f4 v[60:63], v[24:31], v[204:211], v[60:63]
	v_mfma_f32_16x16x128_f8f6f4 v[52:55], v[16:23], v[204:211], v[52:55]
	v_mfma_f32_16x16x128_f8f6f4 v[44:47], v[24:31], v[212:219], v[44:47]
	v_mfma_f32_16x16x128_f8f6f4 v[36:39], v[16:23], v[212:219], v[36:39]
	s_mov_b32 m0, s39
	v_lshl_add_u64 v[176:177], s[30:31], 0, v[168:169]
	s_setprio 0
	s_setprio 1
	v_mfma_f32_16x16x128_f8f6f4 v[88:91], v[8:15], v[188:195], v[88:91]
	global_load_lds_dwordx4 v166, s[34:35]
	v_lshl_add_u64 v[174:175], s[34:35], 0, v[164:165]
	v_lshl_add_u64 v[172:173], s[34:35], 0, v[166:167]
	v_mfma_f32_16x16x128_f8f6f4 v[80:83], v[0:7], v[188:195], v[80:83]
	v_mfma_f32_16x16x128_f8f6f4 v[72:75], v[8:15], v[196:203], v[72:75]
	v_mfma_f32_16x16x128_f8f6f4 v[64:67], v[0:7], v[196:203], v[64:67]
	v_mfma_f32_16x16x128_f8f6f4 v[56:59], v[8:15], v[204:211], v[56:59]
	v_mfma_f32_16x16x128_f8f6f4 v[48:51], v[0:7], v[204:211], v[48:51]
	v_mfma_f32_16x16x128_f8f6f4 v[40:43], v[8:15], v[212:219], v[40:43]
	v_mfma_f32_16x16x128_f8f6f4 v[32:35], v[0:7], v[212:219], v[32:35]
	s_setprio 0
	s_barrier
	ds_read_b128 v[0:3], v182 offset:32768
	ds_read_b128 v[4:7], v182 offset:32784
	ds_read_b128 v[8:11], v182 offset:34816
	ds_read_b128 v[12:15], v182 offset:34832
	ds_read_b128 v[16:19], v182 offset:49152
	ds_read_b128 v[20:23], v182 offset:49168
	ds_read_b128 v[24:27], v182 offset:51200
	ds_read_b128 v[28:31], v182 offset:51216
	s_add_u32 s34, s34, 0x20000
	s_addc_u32 s35, s35, 0
	s_mov_b32 m0, s40
	ds_read_b128 v[188:191], v183 offset:32768
	ds_read_b128 v[192:195], v183 offset:32784
	ds_read_b128 v[196:199], v183 offset:34816
	ds_read_b128 v[200:203], v183 offset:34832
	ds_read_b128 v[204:207], v183 offset:36864
	ds_read_b128 v[208:211], v183 offset:36880
	ds_read_b128 v[212:215], v183 offset:38912
	ds_read_b128 v[216:219], v183 offset:38928
	global_load_lds_dwordx4 v164, s[34:35]
	s_mov_b32 m0, s41
	s_nop 0
	global_load_lds_dwordx4 v166, s[34:35]
	s_waitcnt vmcnt(8)
	s_waitcnt lgkmcnt(0)
	s_barrier
	s_setprio 1
	s_waitcnt lgkmcnt(0)
	v_mfma_f32_16x16x128_f8f6f4 v[156:159], v[0:7], v[188:195], v[156:159]
	v_mfma_f32_16x16x128_f8f6f4 v[148:151], v[8:15], v[188:195], v[148:151]
	v_mfma_f32_16x16x128_f8f6f4 v[140:143], v[0:7], v[196:203], v[140:143]
	v_mfma_f32_16x16x128_f8f6f4 v[132:135], v[8:15], v[196:203], v[132:135]
	v_mfma_f32_16x16x128_f8f6f4 v[124:127], v[0:7], v[204:211], v[124:127]
	v_mfma_f32_16x16x128_f8f6f4 v[116:119], v[8:15], v[204:211], v[116:119]
	v_mfma_f32_16x16x128_f8f6f4 v[108:111], v[0:7], v[212:219], v[108:111]
	v_mfma_f32_16x16x128_f8f6f4 v[100:103], v[8:15], v[212:219], v[100:103]
	s_setprio 0
	s_setprio 1
	v_mfma_f32_16x16x128_f8f6f4 v[152:155], v[16:23], v[188:195], v[152:155]
	v_mfma_f32_16x16x128_f8f6f4 v[144:147], v[24:31], v[188:195], v[144:147]
	v_mfma_f32_16x16x128_f8f6f4 v[136:139], v[16:23], v[196:203], v[136:139]
	v_mfma_f32_16x16x128_f8f6f4 v[128:131], v[24:31], v[196:203], v[128:131]
	v_mfma_f32_16x16x128_f8f6f4 v[120:123], v[16:23], v[204:211], v[120:123]
	v_mfma_f32_16x16x128_f8f6f4 v[112:115], v[24:31], v[204:211], v[112:115]
	v_mfma_f32_16x16x128_f8f6f4 v[104:107], v[16:23], v[212:219], v[104:107]
	v_mfma_f32_16x16x128_f8f6f4 v[96:99], v[24:31], v[212:219], v[96:99]
	s_setprio 0
	s_barrier
	s_mov_b32 m0, s43
	v_lshl_add_u64 v[178:179], v[178:179], 0, s[6:7]
	ds_read_b128 v[188:191], v183 offset:49152
	ds_read_b128 v[192:195], v183 offset:49168
	ds_read_b128 v[196:199], v183 offset:51200
	ds_read_b128 v[200:203], v183 offset:51216
	ds_read_b128 v[204:207], v183 offset:53248
	ds_read_b128 v[208:211], v183 offset:53264
	ds_read_b128 v[212:215], v183 offset:55296
	ds_read_b128 v[216:219], v183 offset:55312
	global_load_lds_dwordx4 v[178:179], off
	v_lshl_add_u64 v[176:177], v[176:177], 0, s[6:7]
	s_mov_b32 m0, s44
	s_add_u32 s30, s30, 0x20080
	global_load_lds_dwordx4 v[176:177], off
	s_addc_u32 s31, s31, 0
	s_mov_b32 m0, s48
	v_lshl_add_u64 v[174:175], v[174:175], 0, s[6:7]
	global_load_lds_dwordx4 v162, s[30:31]
	s_mov_b32 m0, s49
	v_lshl_add_u64 v[172:173], v[172:173], 0, s[6:7]
	global_load_lds_dwordx4 v168, s[30:31]
	s_waitcnt vmcnt(6)
	s_waitcnt lgkmcnt(0)
	s_barrier
	s_setprio 1
	s_waitcnt lgkmcnt(0)
	v_mfma_f32_16x16x128_f8f6f4 v[92:95], v[0:7], v[188:195], v[92:95]
	v_mfma_f32_16x16x128_f8f6f4 v[84:87], v[8:15], v[188:195], v[84:87]
	s_mov_b32 m0, s45
	v_mfma_f32_16x16x128_f8f6f4 v[76:79], v[0:7], v[196:203], v[76:79]
	global_load_lds_dwordx4 v[174:175], off
	v_mfma_f32_16x16x128_f8f6f4 v[68:71], v[8:15], v[196:203], v[68:71]
	v_mfma_f32_16x16x128_f8f6f4 v[60:63], v[0:7], v[204:211], v[60:63]
	v_mfma_f32_16x16x128_f8f6f4 v[52:55], v[8:15], v[204:211], v[52:55]
	v_mfma_f32_16x16x128_f8f6f4 v[44:47], v[0:7], v[212:219], v[44:47]
	v_mfma_f32_16x16x128_f8f6f4 v[36:39], v[8:15], v[212:219], v[36:39]
	s_mov_b32 m0, s47
	s_setprio 0
	s_setprio 1
	v_mfma_f32_16x16x128_f8f6f4 v[88:91], v[16:23], v[188:195], v[88:91]
	global_load_lds_dwordx4 v[172:173], off
	v_mfma_f32_16x16x128_f8f6f4 v[80:83], v[24:31], v[188:195], v[80:83]
	v_mfma_f32_16x16x128_f8f6f4 v[72:75], v[16:23], v[196:203], v[72:75]
	v_mfma_f32_16x16x128_f8f6f4 v[64:67], v[24:31], v[196:203], v[64:67]
	v_mfma_f32_16x16x128_f8f6f4 v[56:59], v[16:23], v[204:211], v[56:59]
	v_mfma_f32_16x16x128_f8f6f4 v[48:51], v[24:31], v[204:211], v[48:51]
	v_mfma_f32_16x16x128_f8f6f4 v[40:43], v[16:23], v[212:219], v[40:43]
	v_mfma_f32_16x16x128_f8f6f4 v[32:35], v[24:31], v[212:219], v[32:35]
	s_setprio 0
	s_barrier
	s_add_i32 s65, s65, 2
	s_add_u32 s28, s28, 0x100
	s_addc_u32 s29, s29, 0
	s_add_u32 s63, s63, 0x100
	s_addc_u32 s64, s64, 0
	s_cmp_gt_u32 s65, 5
	s_cbranch_scc0 .LBB0_1272
	s_nop 15
	s_nop 15
	s_and_b64 vcc, exec, s[8:9]
	s_cbranch_vccz .LBB0_1275
	s_barrier

.LBB0_1349:
	ds_read_b128 v[24:27], v181
	ds_read_b128 v[28:31], v181 offset:16
	ds_read_b128 v[16:19], v181 offset:2048
	ds_read_b128 v[20:23], v181 offset:2064
	ds_read_b128 v[8:11], v181 offset:16384
	ds_read_b128 v[12:15], v181 offset:16400
	ds_read_b128 v[0:3], v181 offset:18432
	ds_read_b128 v[4:7], v181 offset:18448
	s_add_u32 s34, s30, 0xfff90080
	s_addc_u32 s35, s31, -1
	s_cmp_eq_u32 s74, 24
	s_cselect_b32 s37, s1, s35
	s_cselect_b32 s36, s0, s34
	s_cselect_b32 s35, s27, s73
	s_cselect_b32 s34, s26, s72
	s_add_i32 m0, s29, 0xc000
	ds_read_b128 v[172:175], v182
	ds_read_b128 v[176:179], v182 offset:16
	ds_read_b128 v[188:191], v182 offset:2048
	ds_read_b128 v[192:195], v182 offset:2064
	ds_read_b128 v[196:199], v182 offset:4096
	ds_read_b128 v[200:203], v182 offset:4112
	ds_read_b128 v[204:207], v182 offset:6144
	ds_read_b128 v[208:211], v182 offset:6160
	global_load_lds_dwordx4 v162, s[30:31]
	s_add_i32 m0, s29, 0xe000
	v_mov_b32_e32 v167, v163
	global_load_lds_dwordx4 v166, s[30:31]
	s_waitcnt vmcnt(8)
	s_waitcnt lgkmcnt(0)
	s_barrier
	s_setprio 1
	s_waitcnt lgkmcnt(0)
	v_mfma_f32_16x16x128_f8f6f4 v[156:159], v[24:31], v[172:179], v[156:159]
	v_mfma_f32_16x16x128_f8f6f4 v[152:155], v[16:23], v[172:179], v[152:155]
	v_mfma_f32_16x16x128_f8f6f4 v[148:151], v[24:31], v[188:195], v[148:151]
	v_mfma_f32_16x16x128_f8f6f4 v[140:143], v[16:23], v[188:195], v[140:143]
	v_mfma_f32_16x16x128_f8f6f4 v[132:135], v[24:31], v[196:203], v[132:135]
	v_mfma_f32_16x16x128_f8f6f4 v[124:127], v[16:23], v[196:203], v[124:127]
	v_mfma_f32_16x16x128_f8f6f4 v[116:119], v[24:31], v[204:211], v[116:119]
	v_mfma_f32_16x16x128_f8f6f4 v[108:111], v[16:23], v[204:211], v[108:111]
	s_setprio 0
	s_setprio 1
	v_mfma_f32_16x16x128_f8f6f4 v[144:147], v[8:15], v[172:179], v[144:147]
	v_mfma_f32_16x16x128_f8f6f4 v[136:139], v[0:7], v[172:179], v[136:139]
	v_mfma_f32_16x16x128_f8f6f4 v[128:131], v[8:15], v[188:195], v[128:131]
	v_mfma_f32_16x16x128_f8f6f4 v[120:123], v[0:7], v[188:195], v[120:123]
	v_mfma_f32_16x16x128_f8f6f4 v[112:115], v[8:15], v[196:203], v[112:115]
	v_mfma_f32_16x16x128_f8f6f4 v[104:107], v[0:7], v[196:203], v[104:107]
	v_mfma_f32_16x16x128_f8f6f4 v[100:103], v[8:15], v[204:211], v[100:103]
	v_mfma_f32_16x16x128_f8f6f4 v[96:99], v[0:7], v[204:211], v[96:99]
	s_setprio 0
	s_barrier
	s_mov_b32 m0, s39
	ds_read_b128 v[188:191], v182 offset:16384
	ds_read_b128 v[192:195], v182 offset:16400
	ds_read_b128 v[196:199], v182 offset:18432
	ds_read_b128 v[200:203], v182 offset:18448
	ds_read_b128 v[204:207], v182 offset:20480
	ds_read_b128 v[208:211], v182 offset:20496
	ds_read_b128 v[212:215], v182 offset:22528
	ds_read_b128 v[216:219], v182 offset:22544
	global_load_lds_dwordx4 v164, s[34:35]
	s_mov_b32 m0, s40
	s_add_u32 s76, s34, 0x70000
	global_load_lds_dwordx4 v168, s[34:35]
	s_addc_u32 s77, s35, 0
	s_mov_b32 m0, s41
	v_mov_b32_e32 v165, v163
	global_load_lds_dwordx4 v164, s[76:77]
	s_mov_b32 m0, s42
	v_mov_b32_e32 v169, v163
	global_load_lds_dwordx4 v168, s[76:77]
	s_waitcnt vmcnt(6)
	s_waitcnt lgkmcnt(0)
	s_barrier
	s_setprio 1
	s_waitcnt lgkmcnt(0)
	v_mfma_f32_16x16x128_f8f6f4 v[92:95], v[24:31], v[188:195], v[92:95]
	v_mfma_f32_16x16x128_f8f6f4 v[88:91], v[16:23], v[188:195], v[88:91]
	s_mov_b32 m0, s29
	v_lshl_add_u64 v[178:179], s[34:35], 0, v[164:165]
	v_mfma_f32_16x16x128_f8f6f4 v[84:87], v[24:31], v[196:203], v[84:87]
	global_load_lds_dwordx4 v162, s[36:37]
	v_mfma_f32_16x16x128_f8f6f4 v[76:79], v[16:23], v[196:203], v[76:79]
	v_mfma_f32_16x16x128_f8f6f4 v[68:71], v[24:31], v[204:211], v[68:71]
	v_mfma_f32_16x16x128_f8f6f4 v[60:63], v[16:23], v[204:211], v[60:63]
	v_mfma_f32_16x16x128_f8f6f4 v[52:55], v[24:31], v[212:219], v[52:55]
	v_mfma_f32_16x16x128_f8f6f4 v[44:47], v[16:23], v[212:219], v[44:47]
	s_mov_b32 m0, s43
	v_lshl_add_u64 v[176:177], s[34:35], 0, v[168:169]
	s_setprio 0
	s_setprio 1
	v_mfma_f32_16x16x128_f8f6f4 v[80:83], v[8:15], v[188:195], v[80:83]
	global_load_lds_dwordx4 v166, s[36:37]
	v_lshl_add_u64 v[174:175], s[36:37], 0, v[162:163]
	v_lshl_add_u64 v[172:173], s[36:37], 0, v[166:167]
	v_mfma_f32_16x16x128_f8f6f4 v[72:75], v[0:7], v[188:195], v[72:75]
	v_mfma_f32_16x16x128_f8f6f4 v[64:67], v[8:15], v[196:203], v[64:67]
	v_mfma_f32_16x16x128_f8f6f4 v[56:59], v[0:7], v[196:203], v[56:59]
	v_mfma_f32_16x16x128_f8f6f4 v[48:51], v[8:15], v[204:211], v[48:51]
	v_mfma_f32_16x16x128_f8f6f4 v[40:43], v[0:7], v[204:211], v[40:43]
	v_mfma_f32_16x16x128_f8f6f4 v[36:39], v[8:15], v[212:219], v[36:39]
	v_mfma_f32_16x16x128_f8f6f4 v[32:35], v[0:7], v[212:219], v[32:35]
	s_setprio 0
	s_barrier
	ds_read_b128 v[0:3], v181 offset:32768
	ds_read_b128 v[4:7], v181 offset:32784
	ds_read_b128 v[8:11], v181 offset:34816
	ds_read_b128 v[12:15], v181 offset:34832
	ds_read_b128 v[16:19], v181 offset:49152
	ds_read_b128 v[20:23], v181 offset:49168
	ds_read_b128 v[24:27], v181 offset:51200
	ds_read_b128 v[28:31], v181 offset:51216
	s_add_u32 s36, s36, 0x70000
	s_addc_u32 s37, s37, 0
	s_mov_b32 m0, s44
	ds_read_b128 v[188:191], v182 offset:32768
	ds_read_b128 v[192:195], v182 offset:32784
	ds_read_b128 v[196:199], v182 offset:34816
	ds_read_b128 v[200:203], v182 offset:34832
	ds_read_b128 v[204:207], v182 offset:36864
	ds_read_b128 v[208:211], v182 offset:36880
	ds_read_b128 v[212:215], v182 offset:38912
	ds_read_b128 v[216:219], v182 offset:38928
	global_load_lds_dwordx4 v162, s[36:37]
	s_mov_b32 m0, s45
	s_nop 0
	global_load_lds_dwordx4 v166, s[36:37]
	s_waitcnt vmcnt(8)
	s_waitcnt lgkmcnt(0)
	s_barrier
	s_setprio 1
	s_waitcnt lgkmcnt(0)
	v_mfma_f32_16x16x128_f8f6f4 v[156:159], v[0:7], v[188:195], v[156:159]
	v_mfma_f32_16x16x128_f8f6f4 v[152:155], v[8:15], v[188:195], v[152:155]
	v_mfma_f32_16x16x128_f8f6f4 v[148:151], v[0:7], v[196:203], v[148:151]
	v_mfma_f32_16x16x128_f8f6f4 v[140:143], v[8:15], v[196:203], v[140:143]
	v_mfma_f32_16x16x128_f8f6f4 v[132:135], v[0:7], v[204:211], v[132:135]
	v_mfma_f32_16x16x128_f8f6f4 v[124:127], v[8:15], v[204:211], v[124:127]
	v_mfma_f32_16x16x128_f8f6f4 v[116:119], v[0:7], v[212:219], v[116:119]
	v_mfma_f32_16x16x128_f8f6f4 v[108:111], v[8:15], v[212:219], v[108:111]
	s_setprio 0
	s_setprio 1
	v_mfma_f32_16x16x128_f8f6f4 v[144:147], v[16:23], v[188:195], v[144:147]
	v_mfma_f32_16x16x128_f8f6f4 v[136:139], v[24:31], v[188:195], v[136:139]
	v_mfma_f32_16x16x128_f8f6f4 v[128:131], v[16:23], v[196:203], v[128:131]
	v_mfma_f32_16x16x128_f8f6f4 v[120:123], v[24:31], v[196:203], v[120:123]
	v_mfma_f32_16x16x128_f8f6f4 v[112:115], v[16:23], v[204:211], v[112:115]
	v_mfma_f32_16x16x128_f8f6f4 v[104:107], v[24:31], v[204:211], v[104:107]
	v_mfma_f32_16x16x128_f8f6f4 v[100:103], v[16:23], v[212:219], v[100:103]
	v_mfma_f32_16x16x128_f8f6f4 v[96:99], v[24:31], v[212:219], v[96:99]
	s_setprio 0
	s_barrier
	s_mov_b32 m0, s48
	v_lshl_add_u64 v[178:179], v[178:179], 0, s[8:9]
	ds_read_b128 v[188:191], v182 offset:49152
	ds_read_b128 v[192:195], v182 offset:49168
	ds_read_b128 v[196:199], v182 offset:51200
	ds_read_b128 v[200:203], v182 offset:51216
	ds_read_b128 v[204:207], v182 offset:53248
	ds_read_b128 v[208:211], v182 offset:53264
	ds_read_b128 v[212:215], v182 offset:55296
	ds_read_b128 v[216:219], v182 offset:55312
	global_load_lds_dwordx4 v[178:179], off
	v_lshl_add_u64 v[176:177], v[176:177], 0, s[8:9]
	s_mov_b32 m0, s49
	s_add_u32 s34, s34, 0x70080
	global_load_lds_dwordx4 v[176:177], off
	s_addc_u32 s35, s35, 0
	s_mov_b32 m0, s57
	v_lshl_add_u64 v[174:175], v[174:175], 0, s[8:9]
	global_load_lds_dwordx4 v164, s[34:35]
	s_mov_b32 m0, s62
	v_lshl_add_u64 v[172:173], v[172:173], 0, s[8:9]
	global_load_lds_dwordx4 v168, s[34:35]
	s_waitcnt vmcnt(6)
	s_waitcnt lgkmcnt(0)
	s_barrier
	s_setprio 1
	s_waitcnt lgkmcnt(0)
	v_mfma_f32_16x16x128_f8f6f4 v[92:95], v[0:7], v[188:195], v[92:95]
	v_mfma_f32_16x16x128_f8f6f4 v[88:91], v[8:15], v[188:195], v[88:91]
	s_mov_b32 m0, s52
	v_mfma_f32_16x16x128_f8f6f4 v[84:87], v[0:7], v[196:203], v[84:87]
	global_load_lds_dwordx4 v[174:175], off
	v_mfma_f32_16x16x128_f8f6f4 v[76:79], v[8:15], v[196:203], v[76:79]
	v_mfma_f32_16x16x128_f8f6f4 v[68:71], v[0:7], v[204:211], v[68:71]
	v_mfma_f32_16x16x128_f8f6f4 v[60:63], v[8:15], v[204:211], v[60:63]
	v_mfma_f32_16x16x128_f8f6f4 v[52:55], v[0:7], v[212:219], v[52:55]
	v_mfma_f32_16x16x128_f8f6f4 v[44:47], v[8:15], v[212:219], v[44:47]
	s_mov_b32 m0, s53
	s_setprio 0
	s_setprio 1
	v_mfma_f32_16x16x128_f8f6f4 v[80:83], v[16:23], v[188:195], v[80:83]
	global_load_lds_dwordx4 v[172:173], off
	v_mfma_f32_16x16x128_f8f6f4 v[72:75], v[24:31], v[188:195], v[72:75]
	v_mfma_f32_16x16x128_f8f6f4 v[64:67], v[16:23], v[196:203], v[64:67]
	v_mfma_f32_16x16x128_f8f6f4 v[56:59], v[24:31], v[196:203], v[56:59]
	v_mfma_f32_16x16x128_f8f6f4 v[48:51], v[16:23], v[204:211], v[48:51]
	v_mfma_f32_16x16x128_f8f6f4 v[40:43], v[24:31], v[204:211], v[40:43]
	v_mfma_f32_16x16x128_f8f6f4 v[36:39], v[16:23], v[212:219], v[36:39]
	v_mfma_f32_16x16x128_f8f6f4 v[32:35], v[24:31], v[212:219], v[32:35]
	s_setprio 0
	s_barrier
	s_add_i32 s74, s74, 2
	s_add_u32 s30, s30, 0x100
	s_addc_u32 s31, s31, 0
	s_add_u32 s72, s72, 0x100
	s_addc_u32 s73, s73, 0
	s_cmp_gt_u32 s74, 25
	s_cbranch_scc0 .LBB0_1349
	s_nop 15
	s_nop 15
	s_and_b64 vcc, exec, s[10:11]
	s_cbranch_vccz .LBB0_1352
	s_barrier
